# v15 + GEMM mainloops: loop-carried SALU block and exit compare moved in front of the loop-back barrier (back-edge rotation)
# baseline (speedup 1.0000x reference)
; #define PG8_STAGE(bufoff, gbase, voff) do { _Pragma("unroll") for (int _i = 0; _i < 2; ++_i) \
;         __builtin_amdgcn_global_load_lds((const unsigned*)((const char*)(gbase) + (voff)[_i]), (PG8_LAS unsigned*)(lds + (bufoff) + ldsw + _i * 8192), 16, 0, 0); } while (0)
; #define PG8_LDA(dst, b, h) do { _Pragma("unroll") for (int m = 0; m < 4; ++m) _Pragma("unroll") for (int k = 0; k < 2; ++k) dst[m][k] = *(const PG8_LAS bf16x8*)(lds + PG8_SA(b, h) + aoff + m * 2048 + k * 1024); } while (0)
; #define PG8_LDB(dst, b, h) do { _Pragma("unroll") for (int n = 0; n < 2; ++n) _Pragma("unroll") for (int k = 0; k < 2; ++k) dst[n][k] = *(const PG8_LAS bf16x8*)(lds + PG8_SB(b, h) + boff + n * 2048 + k * 1024); } while (0)
; #define PG8_MMA(ai, bj, At, Bt) do { __builtin_amdgcn_s_setprio(1); _Pragma("unroll") for (int m = 0; m < 4; ++m) _Pragma("unroll") for (int n = 0; n < 2; ++n) _Pragma("unroll") for (int k = 0; k < 2; ++k) \
;         acc[ai][bj][m][n] = __builtin_amdgcn_mfma_f32_16x16x32_bf16(Bt[n][k], At[m][k], acc[ai][bj][m][n], 0, 0, 0); __builtin_amdgcn_s_setprio(0); } while (0)
; #define PG8_WAIT_V(n) asm volatile("s_waitcnt vmcnt(" #n ")" ::: "memory")
; #define PG8_WAIT_L(n) asm volatile("s_waitcnt lgkmcnt(" #n ")" ::: "memory")
; #define PG8_BAR __builtin_amdgcn_s_barrier()
; #define PG8_SCHED __builtin_amdgcn_sched_barrier(0)
; template <class Epi, class Sched, bool ALIGN_EPI = false, bool SP2 = false>
; __device__ __forceinline__ void gemm_phase(PG8_LAS unsigned char* lds, const Gemm g, const Sched& S, const Epi& E) {
;     ...
;             PG8_LDB(B0, 0, 0); PG8_LDB(B1, 0, 1); PG8_SCHED; PG8_LDA(At, 0, 0); PG8_STAGE(PG8_SA(1, 1), a1 + hstep, voffA);
;             PG8_WAIT_V(8); PG8_WAIT_L(0); PG8_BAR; PG8_MMA(0, 0, At, B0); PG8_MMA(0, 1, At, B1); PG8_BAR; PG8_SCHED;
;             PG8_LDA(At, 0, 1); PG8_STAGE(PG8_SB(0, 0), b2, voffB); PG8_STAGE(PG8_SB(0, 1), b2 + hstep, voffB); PG8_STAGE(PG8_SA(0, 0), a2, voffA);
;             PG8_WAIT_V(8); PG8_WAIT_L(0); PG8_BAR; PG8_MMA(1, 0, At, B0); PG8_MMA(1, 1, At, B1); PG8_BAR; PG8_SCHED;
.LBB0_343:
	ds_read_b128 v[128:131], v185
	ds_read_b128 v[132:135], v249
	ds_read_b128 v[136:139], v185 offset:2048
	ds_read_b128 v[140:143], v249 offset:2048
	ds_read_b128 v[172:175], v186
	ds_read_b128 v[176:179], v250
	ds_read_b128 v[180:183], v186 offset:2048
	ds_read_b128 v[192:195], v250 offset:2048
	s_add_u32 s0, s78, 0xfffc0080
	s_addc_u32 s1, s79, -1
	s_cmp_eq_u32 s30, 12
	s_cselect_b32 s83, s53, s1
	s_cselect_b32 s82, vcc_lo, s0
	s_cselect_b32 s81, s55, s3
	s_cselect_b32 s80, vcc_hi, s84
	s_add_i32 m0, s92, 0xc000
	ds_read_b128 v[196:199], v187
	ds_read_b128 v[200:203], v251
	ds_read_b128 v[204:207], v187 offset:2048
	ds_read_b128 v[208:211], v251 offset:2048
	ds_read_b128 v[212:215], v187 offset:4096
	ds_read_b128 v[216:219], v251 offset:4096
	ds_read_b128 v[220:223], v187 offset:6144
	ds_read_b128 v[224:227], v251 offset:6144
	global_load_lds_dwordx4 v162, s[78:79]
	s_add_i32 m0, s92, 0xe000
	s_nop 0
	global_load_lds_dwordx4 v166, s[78:79]
	s_waitcnt vmcnt(8)
	s_waitcnt lgkmcnt(0)
	s_barrier
	s_setprio 1
	s_waitcnt lgkmcnt(0)
	v_mfma_f32_16x16x32_bf16 v[124:127], v[128:131], v[196:199], v[124:127]
	v_mfma_f32_16x16x32_bf16 v[120:123], v[136:139], v[196:199], v[120:123]
	v_mfma_f32_16x16x32_bf16 v[116:119], v[128:131], v[204:207], v[116:119]
	v_mfma_f32_16x16x32_bf16 v[112:115], v[136:139], v[204:207], v[112:115]
	v_mfma_f32_16x16x32_bf16 v[100:103], v[128:131], v[212:215], v[100:103]
	v_mfma_f32_16x16x32_bf16 v[96:99], v[136:139], v[212:215], v[96:99]
	v_mfma_f32_16x16x32_bf16 v[84:87], v[128:131], v[220:223], v[84:87]
	v_mfma_f32_16x16x32_bf16 v[80:83], v[136:139], v[220:223], v[80:83]
	v_mfma_f32_16x16x32_bf16 v[124:127], v[132:135], v[200:203], v[124:127]
	v_mfma_f32_16x16x32_bf16 v[120:123], v[140:143], v[200:203], v[120:123]
	v_mfma_f32_16x16x32_bf16 v[116:119], v[132:135], v[208:211], v[116:119]
	v_mfma_f32_16x16x32_bf16 v[112:115], v[140:143], v[208:211], v[112:115]
	v_mfma_f32_16x16x32_bf16 v[100:103], v[132:135], v[216:219], v[100:103]
	v_mfma_f32_16x16x32_bf16 v[96:99], v[140:143], v[216:219], v[96:99]
	v_mfma_f32_16x16x32_bf16 v[84:87], v[132:135], v[224:227], v[84:87]
	v_mfma_f32_16x16x32_bf16 v[80:83], v[140:143], v[224:227], v[80:83]
	s_setprio 0
	s_setprio 1
	v_mfma_f32_16x16x32_bf16 v[108:111], v[172:175], v[196:199], v[108:111]
	v_mfma_f32_16x16x32_bf16 v[104:107], v[180:183], v[196:199], v[104:107]
	v_mfma_f32_16x16x32_bf16 v[92:95], v[172:175], v[204:207], v[92:95]
	v_mfma_f32_16x16x32_bf16 v[88:91], v[180:183], v[204:207], v[88:91]
	v_mfma_f32_16x16x32_bf16 v[76:79], v[172:175], v[212:215], v[76:79]
	v_mfma_f32_16x16x32_bf16 v[72:75], v[180:183], v[212:215], v[72:75]
	v_mfma_f32_16x16x32_bf16 v[68:71], v[172:175], v[220:223], v[68:71]
	v_mfma_f32_16x16x32_bf16 v[64:67], v[180:183], v[220:223], v[64:67]
	v_mfma_f32_16x16x32_bf16 v[108:111], v[176:179], v[200:203], v[108:111]
	v_mfma_f32_16x16x32_bf16 v[104:107], v[192:195], v[200:203], v[104:107]
	v_mfma_f32_16x16x32_bf16 v[92:95], v[176:179], v[208:211], v[92:95]
	v_mfma_f32_16x16x32_bf16 v[88:91], v[192:195], v[208:211], v[88:91]
	v_mfma_f32_16x16x32_bf16 v[76:79], v[176:179], v[216:219], v[76:79]
	v_mfma_f32_16x16x32_bf16 v[72:75], v[192:195], v[216:219], v[72:75]
	v_mfma_f32_16x16x32_bf16 v[68:71], v[176:179], v[224:227], v[68:71]
	v_mfma_f32_16x16x32_bf16 v[64:67], v[192:195], v[224:227], v[64:67]
	s_setprio 0
	s_barrier
	s_add_i32 s0, s8, s51
	s_mov_b32 m0, s0
	ds_read_b128 v[196:199], v187 offset:16384
	ds_read_b128 v[200:203], v251 offset:16384
	ds_read_b128 v[204:207], v187 offset:18432
	ds_read_b128 v[208:211], v251 offset:18432
	ds_read_b128 v[212:215], v187 offset:20480
	ds_read_b128 v[216:219], v251 offset:20480
	ds_read_b128 v[220:223], v187 offset:22528
	ds_read_b128 v[224:227], v251 offset:22528
	global_load_lds_dwordx4 v150, s[80:81]
	s_add_i32 m0, s0, 0x2000
	s_add_u32 s0, s80, 0x40000
	s_addc_u32 s1, s81, 0
	s_add_i32 s31, s9, s51
	global_load_lds_dwordx4 v146, s[80:81]
	s_mov_b32 m0, s31
	s_nop 0
	global_load_lds_dwordx4 v150, s[0:1]
	s_add_i32 m0, s31, 0x2000
	s_nop 0
	global_load_lds_dwordx4 v146, s[0:1]
	s_mov_b32 m0, s92
	s_nop 0
	global_load_lds_dwordx4 v152, s[82:83]
	s_mov_b32 m0, s93
	s_nop 0
	global_load_lds_dwordx4 v148, s[82:83]
	s_waitcnt vmcnt(8)
	s_waitcnt lgkmcnt(0)
	s_barrier
	s_setprio 1
	s_waitcnt lgkmcnt(0)
	v_mfma_f32_16x16x32_bf16 v[60:63], v[128:131], v[196:199], v[60:63]
	v_mfma_f32_16x16x32_bf16 v[56:59], v[136:139], v[196:199], v[56:59]
	v_mfma_f32_16x16x32_bf16 v[52:55], v[128:131], v[204:207], v[52:55]
	v_mfma_f32_16x16x32_bf16 v[48:51], v[136:139], v[204:207], v[48:51]
	v_mfma_f32_16x16x32_bf16 v[36:39], v[128:131], v[212:215], v[36:39]
	v_mfma_f32_16x16x32_bf16 v[32:35], v[136:139], v[212:215], v[32:35]
	v_mfma_f32_16x16x32_bf16 v[20:23], v[128:131], v[220:223], v[20:23]
	v_mfma_f32_16x16x32_bf16 v[16:19], v[136:139], v[220:223], v[16:19]
	v_mfma_f32_16x16x32_bf16 v[60:63], v[132:135], v[200:203], v[60:63]
	v_mfma_f32_16x16x32_bf16 v[56:59], v[140:143], v[200:203], v[56:59]
	v_mfma_f32_16x16x32_bf16 v[52:55], v[132:135], v[208:211], v[52:55]
	v_mfma_f32_16x16x32_bf16 v[48:51], v[140:143], v[208:211], v[48:51]
	v_mfma_f32_16x16x32_bf16 v[36:39], v[132:135], v[216:219], v[36:39]
	v_mfma_f32_16x16x32_bf16 v[32:35], v[140:143], v[216:219], v[32:35]
	v_mfma_f32_16x16x32_bf16 v[20:23], v[132:135], v[224:227], v[20:23]
	v_mfma_f32_16x16x32_bf16 v[16:19], v[140:143], v[224:227], v[16:19]
	s_setprio 0
	s_setprio 1
	v_mfma_f32_16x16x32_bf16 v[44:47], v[172:175], v[196:199], v[44:47]
	v_mfma_f32_16x16x32_bf16 v[40:43], v[180:183], v[196:199], v[40:43]
	v_mfma_f32_16x16x32_bf16 v[28:31], v[172:175], v[204:207], v[28:31]
	v_mfma_f32_16x16x32_bf16 v[24:27], v[180:183], v[204:207], v[24:27]
	v_mfma_f32_16x16x32_bf16 v[12:15], v[172:175], v[212:215], v[12:15]
	v_mfma_f32_16x16x32_bf16 v[8:11], v[180:183], v[212:215], v[8:11]
	v_mfma_f32_16x16x32_bf16 v[4:7], v[172:175], v[220:223], v[4:7]
	v_mfma_f32_16x16x32_bf16 v[0:3], v[180:183], v[220:223], v[0:3]
	v_mfma_f32_16x16x32_bf16 v[44:47], v[176:179], v[200:203], v[44:47]
	v_mfma_f32_16x16x32_bf16 v[40:43], v[192:195], v[200:203], v[40:43]
	v_mfma_f32_16x16x32_bf16 v[28:31], v[176:179], v[208:211], v[28:31]
	v_mfma_f32_16x16x32_bf16 v[24:27], v[192:195], v[208:211], v[24:27]
	v_mfma_f32_16x16x32_bf16 v[12:15], v[176:179], v[216:219], v[12:15]
	v_mfma_f32_16x16x32_bf16 v[8:11], v[192:195], v[216:219], v[8:11]
	v_mfma_f32_16x16x32_bf16 v[4:7], v[176:179], v[224:227], v[4:7]
	v_mfma_f32_16x16x32_bf16 v[0:3], v[192:195], v[224:227], v[0:3]
	s_setprio 0
	s_barrier
; #define PG8_STAGE(bufoff, gbase, voff) do { _Pragma("unroll") for (int _i = 0; _i < 2; ++_i) \
;         __builtin_amdgcn_global_load_lds((const unsigned*)((const char*)(gbase) + (voff)[_i]), (PG8_LAS unsigned*)(lds + (bufoff) + ldsw + _i * 8192), 16, 0, 0); } while (0)
; #define PG8_LDA(dst, b, h) do { _Pragma("unroll") for (int m = 0; m < 4; ++m) _Pragma("unroll") for (int k = 0; k < 2; ++k) dst[m][k] = *(const PG8_LAS bf16x8*)(lds + PG8_SA(b, h) + aoff + m * 2048 + k * 1024); } while (0)
; #define PG8_LDB(dst, b, h) do { _Pragma("unroll") for (int n = 0; n < 2; ++n) _Pragma("unroll") for (int k = 0; k < 2; ++k) dst[n][k] = *(const PG8_LAS bf16x8*)(lds + PG8_SB(b, h) + boff + n * 2048 + k * 1024); } while (0)
; template <class Epi, class Sched, bool ALIGN_EPI = false, bool SP2 = false>
; __device__ __forceinline__ void gemm_phase(PG8_LAS unsigned char* lds, const Gemm g, const Sched& S, const Epi& E) {
;     ...
;         for (int t = 0; t < nt; t += 2) {
;             const bool last = (t == nt - 2);
;             const char* a1 = cA + (size_t)(t + 1) * kstep;
;             const char* a2 = last ? nA : cA + (size_t)(t + 2) * kstep; const char* b2 = last ? nB : cB + (size_t)(t + 2) * kstep;
;             const char* a3 = a2 + kstep; const char* b3 = b2 + kstep;
;             if (last && has_next) S.a_ready(nxt);
;             if constexpr (SP2) {
;             PG8_LDB(B0, 0, 0); PG8_LDB(B1, 0, 1); PG8_SCHED; PG8_LDA(At, 0, 0); PG8_STAGE(PG8_SA(1, 1), a1 + hstep, voffA);
;             PG8_WAIT_V(8); PG8_WAIT_L(0); PG8_BAR; PG8_MMA(0, 0, At, B0); PG8_MMA(0, 1, At, B1); PG8_BAR; PG8_SCHED;
;             PG8_LDA(At, 0, 1); PG8_STAGE(PG8_SB(0, 0), b2, voffB); PG8_STAGE(PG8_SB(0, 1), b2 + hstep, voffB); PG8_STAGE(PG8_SA(0, 0), a2, voffA);
;             PG8_WAIT_V(8); PG8_WAIT_L(0); PG8_BAR; PG8_MMA(1, 0, At, B0); PG8_MMA(1, 1, At, B1); PG8_BAR; PG8_SCHED;
;             PG8_LDB(B0, 1, 0); PG8_LDB(B1, 1, 1); PG8_SCHED; PG8_LDA(At, 1, 0); PG8_STAGE(PG8_SA(0, 1), a2 + hstep, voffA);
;             PG8_WAIT_V(8); PG8_WAIT_L(0); PG8_BAR; PG8_MMA(0, 0, At, B0); PG8_MMA(0, 1, At, B1); PG8_BAR; PG8_SCHED;
;             PG8_LDA(At, 1, 1); PG8_STAGE(PG8_SB(1, 0), b3, voffB); PG8_STAGE(PG8_SB(1, 1), b3 + hstep, voffB); PG8_STAGE(PG8_SA(1, 0), a3, voffA);
;             PG8_WAIT_V(8); PG8_WAIT_L(0); PG8_BAR; PG8_MMA(1, 0, At, B0); PG8_MMA(1, 1, At, B1); PG8_BAR; PG8_SCHED;
	s_add_i32 s31, 0, 0x18000
	s_add_i32 s91, 0, 0x1c000
	v_add_u32_e32 v140, s31, v157
	v_xor_b32_e32 v252, 64, v140
	v_add_u32_e32 v154, s91, v157
	v_xor_b32_e32 v253, 64, v154
	ds_read_b128 v[128:131], v140
	ds_read_b128 v[132:135], v252
	ds_read_b128 v[136:139], v140 offset:2048
	ds_read_b128 v[140:143], v252 offset:2048
	ds_read_b128 v[172:175], v154
	ds_read_b128 v[176:179], v253
	ds_read_b128 v[180:183], v154 offset:2048
	ds_read_b128 v[192:195], v253 offset:2048
	s_add_u32 s0, s82, 0x40000
	s_addc_u32 s1, s83, 0
	s_mov_b32 m0, s94
	ds_read_b128 v[196:199], v187 offset:32768
	ds_read_b128 v[200:203], v251 offset:32768
	ds_read_b128 v[204:207], v187 offset:34816
	ds_read_b128 v[208:211], v251 offset:34816
	ds_read_b128 v[212:215], v187 offset:36864
	ds_read_b128 v[216:219], v251 offset:36864
	ds_read_b128 v[220:223], v187 offset:38912
	ds_read_b128 v[224:227], v251 offset:38912
	global_load_lds_dwordx4 v152, s[0:1]
	s_mov_b32 m0, s95
	s_nop 0
	global_load_lds_dwordx4 v148, s[0:1]
	s_add_u32 s100, s80, 0x80
	s_addc_u32 s101, s81, 0
	s_add_u32 s98, s82, 0x80
	s_addc_u32 s99, s83, 0
	s_waitcnt vmcnt(8)
	s_waitcnt lgkmcnt(0)
	s_barrier
	s_setprio 1
	s_waitcnt lgkmcnt(0)
	v_mfma_f32_16x16x32_bf16 v[124:127], v[128:131], v[196:199], v[124:127]
	v_mfma_f32_16x16x32_bf16 v[120:123], v[136:139], v[196:199], v[120:123]
	v_mfma_f32_16x16x32_bf16 v[116:119], v[128:131], v[204:207], v[116:119]
	v_mfma_f32_16x16x32_bf16 v[112:115], v[136:139], v[204:207], v[112:115]
	v_mfma_f32_16x16x32_bf16 v[100:103], v[128:131], v[212:215], v[100:103]
	v_mfma_f32_16x16x32_bf16 v[96:99], v[136:139], v[212:215], v[96:99]
	v_mfma_f32_16x16x32_bf16 v[84:87], v[128:131], v[220:223], v[84:87]
	v_mfma_f32_16x16x32_bf16 v[80:83], v[136:139], v[220:223], v[80:83]
	v_mfma_f32_16x16x32_bf16 v[124:127], v[132:135], v[200:203], v[124:127]
	v_mfma_f32_16x16x32_bf16 v[120:123], v[140:143], v[200:203], v[120:123]
	v_mfma_f32_16x16x32_bf16 v[116:119], v[132:135], v[208:211], v[116:119]
	v_mfma_f32_16x16x32_bf16 v[112:115], v[140:143], v[208:211], v[112:115]
	v_mfma_f32_16x16x32_bf16 v[100:103], v[132:135], v[216:219], v[100:103]
	v_mfma_f32_16x16x32_bf16 v[96:99], v[140:143], v[216:219], v[96:99]
	v_mfma_f32_16x16x32_bf16 v[84:87], v[132:135], v[224:227], v[84:87]
	v_mfma_f32_16x16x32_bf16 v[80:83], v[140:143], v[224:227], v[80:83]
	s_setprio 0
	s_setprio 1
	v_mfma_f32_16x16x32_bf16 v[108:111], v[172:175], v[196:199], v[108:111]
	v_mfma_f32_16x16x32_bf16 v[104:107], v[180:183], v[196:199], v[104:107]
	v_mfma_f32_16x16x32_bf16 v[92:95], v[172:175], v[204:207], v[92:95]
	v_mfma_f32_16x16x32_bf16 v[88:91], v[180:183], v[204:207], v[88:91]
	v_mfma_f32_16x16x32_bf16 v[76:79], v[172:175], v[212:215], v[76:79]
	v_mfma_f32_16x16x32_bf16 v[72:75], v[180:183], v[212:215], v[72:75]
	v_mfma_f32_16x16x32_bf16 v[68:71], v[172:175], v[220:223], v[68:71]
	v_mfma_f32_16x16x32_bf16 v[64:67], v[180:183], v[220:223], v[64:67]
	v_mfma_f32_16x16x32_bf16 v[108:111], v[176:179], v[200:203], v[108:111]
	v_mfma_f32_16x16x32_bf16 v[104:107], v[192:195], v[200:203], v[104:107]
	v_mfma_f32_16x16x32_bf16 v[92:95], v[176:179], v[208:211], v[92:95]
	v_mfma_f32_16x16x32_bf16 v[88:91], v[192:195], v[208:211], v[88:91]
	v_mfma_f32_16x16x32_bf16 v[76:79], v[176:179], v[216:219], v[76:79]
	v_mfma_f32_16x16x32_bf16 v[72:75], v[192:195], v[216:219], v[72:75]
	v_mfma_f32_16x16x32_bf16 v[68:71], v[176:179], v[224:227], v[68:71]
	v_mfma_f32_16x16x32_bf16 v[64:67], v[192:195], v[224:227], v[64:67]
	s_setprio 0
	s_barrier
	s_add_i32 s0, s31, s51
	s_mov_b32 m0, s0
	ds_read_b128 v[196:199], v187 offset:49152
	ds_read_b128 v[200:203], v251 offset:49152
	ds_read_b128 v[204:207], v187 offset:51200
	ds_read_b128 v[208:211], v251 offset:51200
	ds_read_b128 v[212:215], v187 offset:53248
	ds_read_b128 v[216:219], v251 offset:53248
	ds_read_b128 v[220:223], v187 offset:55296
	ds_read_b128 v[224:227], v251 offset:55296
	global_load_lds_dwordx4 v150, s[100:101]
	s_add_i32 m0, s0, 0x2000
	s_add_u32 s0, s80, 0x40080
	s_addc_u32 s1, s81, 0
	s_add_i32 s31, s91, s51
	global_load_lds_dwordx4 v146, s[100:101]
	s_mov_b32 m0, s31
	s_nop 0
	global_load_lds_dwordx4 v150, s[0:1]
	s_add_i32 m0, s31, 0x2000
	s_nop 0
	global_load_lds_dwordx4 v146, s[0:1]
	s_mov_b32 m0, s97
	s_nop 0
	global_load_lds_dwordx4 v152, s[98:99]
	s_mov_b32 m0, s34
	s_nop 0
	global_load_lds_dwordx4 v148, s[98:99]
	s_waitcnt vmcnt(8)
	s_waitcnt lgkmcnt(0)
	s_barrier
	s_setprio 1
	s_waitcnt lgkmcnt(0)
	v_mfma_f32_16x16x32_bf16 v[60:63], v[128:131], v[196:199], v[60:63]
	v_mfma_f32_16x16x32_bf16 v[56:59], v[136:139], v[196:199], v[56:59]
	v_mfma_f32_16x16x32_bf16 v[52:55], v[128:131], v[204:207], v[52:55]
	v_mfma_f32_16x16x32_bf16 v[48:51], v[136:139], v[204:207], v[48:51]
	v_mfma_f32_16x16x32_bf16 v[36:39], v[128:131], v[212:215], v[36:39]
	v_mfma_f32_16x16x32_bf16 v[32:35], v[136:139], v[212:215], v[32:35]
	v_mfma_f32_16x16x32_bf16 v[20:23], v[128:131], v[220:223], v[20:23]
	v_mfma_f32_16x16x32_bf16 v[16:19], v[136:139], v[220:223], v[16:19]
	v_mfma_f32_16x16x32_bf16 v[60:63], v[132:135], v[200:203], v[60:63]
	v_mfma_f32_16x16x32_bf16 v[56:59], v[140:143], v[200:203], v[56:59]
	v_mfma_f32_16x16x32_bf16 v[52:55], v[132:135], v[208:211], v[52:55]
	v_mfma_f32_16x16x32_bf16 v[48:51], v[140:143], v[208:211], v[48:51]
	v_mfma_f32_16x16x32_bf16 v[36:39], v[132:135], v[216:219], v[36:39]
	v_mfma_f32_16x16x32_bf16 v[32:35], v[140:143], v[216:219], v[32:35]
	v_mfma_f32_16x16x32_bf16 v[20:23], v[132:135], v[224:227], v[20:23]
	v_mfma_f32_16x16x32_bf16 v[16:19], v[140:143], v[224:227], v[16:19]
	s_setprio 0
	s_setprio 1
	v_mfma_f32_16x16x32_bf16 v[44:47], v[172:175], v[196:199], v[44:47]
	v_mfma_f32_16x16x32_bf16 v[40:43], v[180:183], v[196:199], v[40:43]
	v_mfma_f32_16x16x32_bf16 v[28:31], v[172:175], v[204:207], v[28:31]
	v_mfma_f32_16x16x32_bf16 v[24:27], v[180:183], v[204:207], v[24:27]
	v_mfma_f32_16x16x32_bf16 v[12:15], v[172:175], v[212:215], v[12:15]
	v_mfma_f32_16x16x32_bf16 v[8:11], v[180:183], v[212:215], v[8:11]
	v_mfma_f32_16x16x32_bf16 v[4:7], v[172:175], v[220:223], v[4:7]
	v_mfma_f32_16x16x32_bf16 v[0:3], v[180:183], v[220:223], v[0:3]
	v_mfma_f32_16x16x32_bf16 v[44:47], v[176:179], v[200:203], v[44:47]
	v_mfma_f32_16x16x32_bf16 v[40:43], v[192:195], v[200:203], v[40:43]
	v_mfma_f32_16x16x32_bf16 v[28:31], v[176:179], v[208:211], v[28:31]
	v_mfma_f32_16x16x32_bf16 v[24:27], v[192:195], v[208:211], v[24:27]
	v_mfma_f32_16x16x32_bf16 v[12:15], v[176:179], v[216:219], v[12:15]
	v_mfma_f32_16x16x32_bf16 v[8:11], v[192:195], v[216:219], v[8:11]
	v_mfma_f32_16x16x32_bf16 v[4:7], v[176:179], v[224:227], v[4:7]
	v_mfma_f32_16x16x32_bf16 v[0:3], v[192:195], v[224:227], v[0:3]
	s_setprio 0
	s_add_i32 s30, s30, 2
	s_add_u32 s78, s78, 0x100
	s_addc_u32 s79, s79, 0
	s_add_u32 s84, s84, 0x100
	s_addc_u32 s3, s3, 0
	s_cmp_gt_u32 s30, 13
	s_barrier
	s_cbranch_scc0 .LBB0_343
	s_and_b64 vcc, exec, s[48:49]
	s_cbranch_vccz .LBB0_346
	s_barrier

; #define PG8_STAGE(bufoff, gbase, voff) do { _Pragma("unroll") for (int _i = 0; _i < 2; ++_i) \
;         __builtin_amdgcn_global_load_lds((const unsigned*)((const char*)(gbase) + (voff)[_i]), (PG8_LAS unsigned*)(lds + (bufoff) + ldsw + _i * 8192), 16, 0, 0); } while (0)
; #define PG8_LDA(dst, b, h) do { _Pragma("unroll") for (int m = 0; m < 4; ++m) _Pragma("unroll") for (int k = 0; k < 2; ++k) dst[m][k] = *(const PG8_LAS bf16x8*)(lds + PG8_SA(b, h) + aoff + m * 2048 + k * 1024); } while (0)
; #define PG8_LDB(dst, b, h) do { _Pragma("unroll") for (int n = 0; n < 2; ++n) _Pragma("unroll") for (int k = 0; k < 2; ++k) dst[n][k] = *(const PG8_LAS bf16x8*)(lds + PG8_SB(b, h) + boff + n * 2048 + k * 1024); } while (0)
; #define PG8_MMA(ai, bj, At, Bt) do { __builtin_amdgcn_s_setprio(1); _Pragma("unroll") for (int m = 0; m < 4; ++m) _Pragma("unroll") for (int n = 0; n < 2; ++n) _Pragma("unroll") for (int k = 0; k < 2; ++k) \
;         acc[ai][bj][m][n] = __builtin_amdgcn_mfma_f32_16x16x32_bf16(Bt[n][k], At[m][k], acc[ai][bj][m][n], 0, 0, 0); __builtin_amdgcn_s_setprio(0); } while (0)
; #define PG8_WAIT_V(n) asm volatile("s_waitcnt vmcnt(" #n ")" ::: "memory")
; #define PG8_WAIT_L(n) asm volatile("s_waitcnt lgkmcnt(" #n ")" ::: "memory")
; #define PG8_BAR __builtin_amdgcn_s_barrier()
; #define PG8_SCHED __builtin_amdgcn_sched_barrier(0)
; template <class Epi, class Sched, bool ALIGN_EPI = false, bool SP2 = false>
; __device__ __forceinline__ void gemm_phase(PG8_LAS unsigned char* lds, const Gemm g, const Sched& S, const Epi& E) {
;     ...
;             PG8_LDB(B0, 0, 0); PG8_LDB(B1, 0, 1); PG8_SCHED; PG8_LDA(At, 0, 0); PG8_STAGE(PG8_SA(1, 1), a1 + hstep, voffA);
;             PG8_WAIT_V(8); PG8_WAIT_L(0); PG8_BAR; PG8_MMA(0, 0, At, B0); PG8_MMA(0, 1, At, B1); PG8_BAR; PG8_SCHED;
;             PG8_LDA(At, 0, 1); PG8_STAGE(PG8_SB(0, 0), b2, voffB); PG8_STAGE(PG8_SB(0, 1), b2 + hstep, voffB); PG8_STAGE(PG8_SA(0, 0), a2, voffA);
;             PG8_WAIT_V(8); PG8_WAIT_L(0); PG8_BAR; PG8_MMA(1, 0, At, B0); PG8_MMA(1, 1, At, B1); PG8_BAR; PG8_SCHED;
.LBB0_573:
	v_add_u32_e32 v1, s74, v183
	v_xor_b32_e32 v252, 64, v1
	ds_read_b128 v[132:135], v1
	ds_read_b128 v[136:139], v252
	ds_read_b128 v[140:143], v1 offset:2048
	ds_read_b128 v[144:147], v252 offset:2048
	v_add_u32_e32 v1, s75, v183
	v_xor_b32_e32 v252, 64, v1
	ds_read_b128 v[148:151], v1
	ds_read_b128 v[152:155], v252
	ds_read_b128 v[156:159], v1 offset:2048
	ds_read_b128 v[160:163], v252 offset:2048
	s_add_u32 s50, s48, 0xfffe0080
	s_addc_u32 s51, s49, -1
	s_cmp_eq_u32 s84, 4
	s_cselect_b32 s53, s31, s51
	s_cselect_b32 s52, s39, s50
	s_cselect_b32 s51, s41, s83
	s_cselect_b32 s50, s47, s82
	s_add_i32 m0, s34, 0xc000
	ds_read_b128 v[186:189], v185
	ds_read_b128 v[190:193], v251
	ds_read_b128 v[194:197], v185 offset:2048
	ds_read_b128 v[198:201], v251 offset:2048
	ds_read_b128 v[202:205], v185 offset:4096
	ds_read_b128 v[206:209], v251 offset:4096
	ds_read_b128 v[210:213], v185 offset:6144
	ds_read_b128 v[214:217], v251 offset:6144
	global_load_lds_dwordx4 v174, s[48:49]
	s_add_i32 m0, s34, 0xe000
	s_nop 0
	global_load_lds_dwordx4 v176, s[48:49]
	s_waitcnt vmcnt(8)
	s_waitcnt lgkmcnt(0)
	s_barrier
	s_setprio 1
	s_waitcnt lgkmcnt(0)
	v_mfma_f32_16x16x32_bf16 v[128:131], v[132:135], v[186:189], v[128:131]
	v_mfma_f32_16x16x32_bf16 v[124:127], v[140:143], v[186:189], v[124:127]
	v_mfma_f32_16x16x32_bf16 v[120:123], v[132:135], v[194:197], v[120:123]
	v_mfma_f32_16x16x32_bf16 v[116:119], v[140:143], v[194:197], v[116:119]
	v_mfma_f32_16x16x32_bf16 v[112:115], v[132:135], v[202:205], v[112:115]
	v_mfma_f32_16x16x32_bf16 v[108:111], v[140:143], v[202:205], v[108:111]
	v_mfma_f32_16x16x32_bf16 v[104:107], v[132:135], v[210:213], v[104:107]
	v_mfma_f32_16x16x32_bf16 v[100:103], v[140:143], v[210:213], v[100:103]
	v_mfma_f32_16x16x32_bf16 v[128:131], v[136:139], v[190:193], v[128:131]
	v_mfma_f32_16x16x32_bf16 v[124:127], v[144:147], v[190:193], v[124:127]
	v_mfma_f32_16x16x32_bf16 v[120:123], v[136:139], v[198:201], v[120:123]
	v_mfma_f32_16x16x32_bf16 v[116:119], v[144:147], v[198:201], v[116:119]
	v_mfma_f32_16x16x32_bf16 v[112:115], v[136:139], v[206:209], v[112:115]
	v_mfma_f32_16x16x32_bf16 v[108:111], v[144:147], v[206:209], v[108:111]
	v_mfma_f32_16x16x32_bf16 v[104:107], v[136:139], v[214:217], v[104:107]
	v_mfma_f32_16x16x32_bf16 v[100:103], v[144:147], v[214:217], v[100:103]
	s_setprio 0
	s_setprio 1
	v_mfma_f32_16x16x32_bf16 v[96:99], v[148:151], v[186:189], v[96:99]
	v_mfma_f32_16x16x32_bf16 v[92:95], v[156:159], v[186:189], v[92:95]
	v_mfma_f32_16x16x32_bf16 v[88:91], v[148:151], v[194:197], v[88:91]
	v_mfma_f32_16x16x32_bf16 v[84:87], v[156:159], v[194:197], v[84:87]
	v_mfma_f32_16x16x32_bf16 v[80:83], v[148:151], v[202:205], v[80:83]
	v_mfma_f32_16x16x32_bf16 v[76:79], v[156:159], v[202:205], v[76:79]
	v_mfma_f32_16x16x32_bf16 v[72:75], v[148:151], v[210:213], v[72:75]
	v_mfma_f32_16x16x32_bf16 v[68:71], v[156:159], v[210:213], v[68:71]
	v_mfma_f32_16x16x32_bf16 v[96:99], v[152:155], v[190:193], v[96:99]
	v_mfma_f32_16x16x32_bf16 v[92:95], v[160:163], v[190:193], v[92:95]
	v_mfma_f32_16x16x32_bf16 v[88:91], v[152:155], v[198:201], v[88:91]
	v_mfma_f32_16x16x32_bf16 v[84:87], v[160:163], v[198:201], v[84:87]
	v_mfma_f32_16x16x32_bf16 v[80:83], v[152:155], v[206:209], v[80:83]
	v_mfma_f32_16x16x32_bf16 v[76:79], v[160:163], v[206:209], v[76:79]
	v_mfma_f32_16x16x32_bf16 v[72:75], v[152:155], v[214:217], v[72:75]
	v_mfma_f32_16x16x32_bf16 v[68:71], v[160:163], v[214:217], v[68:71]
	s_setprio 0
	s_barrier
	s_add_i32 s85, s74, s7
	s_mov_b32 m0, s85
	ds_read_b128 v[186:189], v185 offset:16384
	ds_read_b128 v[190:193], v251 offset:16384
	ds_read_b128 v[194:197], v185 offset:18432
	ds_read_b128 v[198:201], v251 offset:18432
	ds_read_b128 v[202:205], v185 offset:20480
	ds_read_b128 v[206:209], v251 offset:20480
	ds_read_b128 v[210:213], v185 offset:22528
	ds_read_b128 v[214:217], v251 offset:22528
	global_load_lds_dwordx4 v168, s[50:51]
	s_add_i32 m0, s85, 0x2000
	s_add_u32 s86, s50, 0x20000
	s_addc_u32 s87, s51, 0
	s_add_i32 s85, s75, s7
	global_load_lds_dwordx4 v172, s[50:51]
	s_mov_b32 m0, s85
	s_nop 0
	global_load_lds_dwordx4 v168, s[86:87]
	s_add_i32 m0, s85, 0x2000
	s_nop 0
	global_load_lds_dwordx4 v172, s[86:87]
	s_mov_b32 m0, s34
	s_nop 0
	global_load_lds_dwordx4 v166, s[52:53]
	s_mov_b32 m0, s35
	s_nop 0
	global_load_lds_dwordx4 v170, s[52:53]
	s_waitcnt vmcnt(8)
	s_waitcnt lgkmcnt(0)
	s_barrier
	s_setprio 1
	s_waitcnt lgkmcnt(0)
	v_mfma_f32_16x16x32_bf16 v[64:67], v[132:135], v[186:189], v[64:67]
	v_mfma_f32_16x16x32_bf16 v[60:63], v[140:143], v[186:189], v[60:63]
	v_mfma_f32_16x16x32_bf16 v[56:59], v[132:135], v[194:197], v[56:59]
	v_mfma_f32_16x16x32_bf16 v[52:55], v[140:143], v[194:197], v[52:55]
	v_mfma_f32_16x16x32_bf16 v[48:51], v[132:135], v[202:205], v[48:51]
	v_mfma_f32_16x16x32_bf16 v[44:47], v[140:143], v[202:205], v[44:47]
	v_mfma_f32_16x16x32_bf16 v[40:43], v[132:135], v[210:213], v[40:43]
	v_mfma_f32_16x16x32_bf16 v[36:39], v[140:143], v[210:213], v[36:39]
	v_mfma_f32_16x16x32_bf16 v[64:67], v[136:139], v[190:193], v[64:67]
	v_mfma_f32_16x16x32_bf16 v[60:63], v[144:147], v[190:193], v[60:63]
	v_mfma_f32_16x16x32_bf16 v[56:59], v[136:139], v[198:201], v[56:59]
	v_mfma_f32_16x16x32_bf16 v[52:55], v[144:147], v[198:201], v[52:55]
	v_mfma_f32_16x16x32_bf16 v[48:51], v[136:139], v[206:209], v[48:51]
	v_mfma_f32_16x16x32_bf16 v[44:47], v[144:147], v[206:209], v[44:47]
	v_mfma_f32_16x16x32_bf16 v[40:43], v[136:139], v[214:217], v[40:43]
	v_mfma_f32_16x16x32_bf16 v[36:39], v[144:147], v[214:217], v[36:39]
	s_setprio 0
	s_setprio 1
	v_mfma_f32_16x16x32_bf16 v[32:35], v[148:151], v[186:189], v[32:35]
	v_mfma_f32_16x16x32_bf16 v[28:31], v[156:159], v[186:189], v[28:31]
	v_mfma_f32_16x16x32_bf16 v[24:27], v[148:151], v[194:197], v[24:27]
	v_mfma_f32_16x16x32_bf16 v[20:23], v[156:159], v[194:197], v[20:23]
	v_mfma_f32_16x16x32_bf16 v[16:19], v[148:151], v[202:205], v[16:19]
	v_mfma_f32_16x16x32_bf16 v[12:15], v[156:159], v[202:205], v[12:15]
	v_mfma_f32_16x16x32_bf16 v[8:11], v[148:151], v[210:213], v[8:11]
	v_mfma_f32_16x16x32_bf16 v[2:5], v[156:159], v[210:213], v[4:7]
	v_mfma_f32_16x16x32_bf16 v[32:35], v[152:155], v[190:193], v[32:35]
	v_mfma_f32_16x16x32_bf16 v[28:31], v[160:163], v[190:193], v[28:31]
	v_mfma_f32_16x16x32_bf16 v[24:27], v[152:155], v[198:201], v[24:27]
	v_mfma_f32_16x16x32_bf16 v[20:23], v[160:163], v[198:201], v[20:23]
	v_mfma_f32_16x16x32_bf16 v[16:19], v[152:155], v[206:209], v[16:19]
	v_mfma_f32_16x16x32_bf16 v[12:15], v[160:163], v[206:209], v[12:15]
	v_mfma_f32_16x16x32_bf16 v[8:11], v[152:155], v[214:217], v[8:11]
	v_mfma_f32_16x16x32_bf16 v[2:5], v[160:163], v[214:217], v[2:5]
	s_setprio 0
	s_barrier
; #define PG8_STAGE(bufoff, gbase, voff) do { _Pragma("unroll") for (int _i = 0; _i < 2; ++_i) \
;         __builtin_amdgcn_global_load_lds((const unsigned*)((const char*)(gbase) + (voff)[_i]), (PG8_LAS unsigned*)(lds + (bufoff) + ldsw + _i * 8192), 16, 0, 0); } while (0)
; #define PG8_LDA(dst, b, h) do { _Pragma("unroll") for (int m = 0; m < 4; ++m) _Pragma("unroll") for (int k = 0; k < 2; ++k) dst[m][k] = *(const PG8_LAS bf16x8*)(lds + PG8_SA(b, h) + aoff + m * 2048 + k * 1024); } while (0)
; #define PG8_LDB(dst, b, h) do { _Pragma("unroll") for (int n = 0; n < 2; ++n) _Pragma("unroll") for (int k = 0; k < 2; ++k) dst[n][k] = *(const PG8_LAS bf16x8*)(lds + PG8_SB(b, h) + boff + n * 2048 + k * 1024); } while (0)
; template <class Epi, class Sched, bool ALIGN_EPI = false, bool SP2 = false>
; __device__ __forceinline__ void gemm_phase(PG8_LAS unsigned char* lds, const Gemm g, const Sched& S, const Epi& E) {
;     ...
;         for (int t = 0; t < nt; t += 2) {
;             const bool last = (t == nt - 2);
;             const char* a1 = cA + (size_t)(t + 1) * kstep;
;             const char* a2 = last ? nA : cA + (size_t)(t + 2) * kstep; const char* b2 = last ? nB : cB + (size_t)(t + 2) * kstep;
;             const char* a3 = a2 + kstep; const char* b3 = b2 + kstep;
;             if (last && has_next) S.a_ready(nxt);
;             if constexpr (SP2) {
;             PG8_LDB(B0, 0, 0); PG8_LDB(B1, 0, 1); PG8_SCHED; PG8_LDA(At, 0, 0); PG8_STAGE(PG8_SA(1, 1), a1 + hstep, voffA);
;             PG8_WAIT_V(8); PG8_WAIT_L(0); PG8_BAR; PG8_MMA(0, 0, At, B0); PG8_MMA(0, 1, At, B1); PG8_BAR; PG8_SCHED;
;             PG8_LDA(At, 0, 1); PG8_STAGE(PG8_SB(0, 0), b2, voffB); PG8_STAGE(PG8_SB(0, 1), b2 + hstep, voffB); PG8_STAGE(PG8_SA(0, 0), a2, voffA);
;             PG8_WAIT_V(8); PG8_WAIT_L(0); PG8_BAR; PG8_MMA(1, 0, At, B0); PG8_MMA(1, 1, At, B1); PG8_BAR; PG8_SCHED;
;             PG8_LDB(B0, 1, 0); PG8_LDB(B1, 1, 1); PG8_SCHED; PG8_LDA(At, 1, 0); PG8_STAGE(PG8_SA(0, 1), a2 + hstep, voffA);
;             PG8_WAIT_V(8); PG8_WAIT_L(0); PG8_BAR; PG8_MMA(0, 0, At, B0); PG8_MMA(0, 1, At, B1); PG8_BAR; PG8_SCHED;
;             PG8_LDA(At, 1, 1); PG8_STAGE(PG8_SB(1, 0), b3, voffB); PG8_STAGE(PG8_SB(1, 1), b3 + hstep, voffB); PG8_STAGE(PG8_SA(1, 0), a3, voffA);
;             PG8_WAIT_V(8); PG8_WAIT_L(0); PG8_BAR; PG8_MMA(1, 0, At, B0); PG8_MMA(1, 1, At, B1); PG8_BAR; PG8_SCHED;
	s_add_i32 s85, 0, 0x18000
	v_add_u32_e32 v1, s85, v183
	v_xor_b32_e32 v252, 64, v1
	s_add_i32 s86, 0, 0x1c000
	ds_read_b128 v[132:135], v1
	ds_read_b128 v[136:139], v252
	ds_read_b128 v[140:143], v1 offset:2048
	ds_read_b128 v[144:147], v252 offset:2048
	v_add_u32_e32 v1, s86, v183
	v_xor_b32_e32 v252, 64, v1
	ds_read_b128 v[148:151], v1
	ds_read_b128 v[152:155], v252
	ds_read_b128 v[156:159], v1 offset:2048
	ds_read_b128 v[160:163], v252 offset:2048
	s_add_u32 s52, s52, 0x20000
	s_addc_u32 s53, s53, 0
	s_mov_b32 m0, s58
	ds_read_b128 v[186:189], v185 offset:32768
	ds_read_b128 v[190:193], v251 offset:32768
	ds_read_b128 v[194:197], v185 offset:34816
	ds_read_b128 v[198:201], v251 offset:34816
	ds_read_b128 v[202:205], v185 offset:36864
	ds_read_b128 v[206:209], v251 offset:36864
	ds_read_b128 v[210:213], v185 offset:38912
	ds_read_b128 v[214:217], v251 offset:38912
	global_load_lds_dwordx4 v166, s[52:53]
	s_mov_b32 m0, s59
	s_nop 0
	global_load_lds_dwordx4 v170, s[52:53]
	s_add_u32 s100, s50, 0x80
	s_addc_u32 s101, s51, 0
	s_sub_u32 s98, s52, 0x1ff80
	s_subb_u32 s99, s53, 0
	s_waitcnt vmcnt(8)
	s_waitcnt lgkmcnt(0)
	s_barrier
	s_setprio 1
	s_waitcnt lgkmcnt(0)
	v_mfma_f32_16x16x32_bf16 v[128:131], v[132:135], v[186:189], v[128:131]
	v_mfma_f32_16x16x32_bf16 v[124:127], v[140:143], v[186:189], v[124:127]
	v_mfma_f32_16x16x32_bf16 v[120:123], v[132:135], v[194:197], v[120:123]
	v_mfma_f32_16x16x32_bf16 v[116:119], v[140:143], v[194:197], v[116:119]
	v_mfma_f32_16x16x32_bf16 v[112:115], v[132:135], v[202:205], v[112:115]
	v_mfma_f32_16x16x32_bf16 v[108:111], v[140:143], v[202:205], v[108:111]
	v_mfma_f32_16x16x32_bf16 v[104:107], v[132:135], v[210:213], v[104:107]
	v_mfma_f32_16x16x32_bf16 v[100:103], v[140:143], v[210:213], v[100:103]
	v_mfma_f32_16x16x32_bf16 v[128:131], v[136:139], v[190:193], v[128:131]
	v_mfma_f32_16x16x32_bf16 v[124:127], v[144:147], v[190:193], v[124:127]
	v_mfma_f32_16x16x32_bf16 v[120:123], v[136:139], v[198:201], v[120:123]
	v_mfma_f32_16x16x32_bf16 v[116:119], v[144:147], v[198:201], v[116:119]
	v_mfma_f32_16x16x32_bf16 v[112:115], v[136:139], v[206:209], v[112:115]
	v_mfma_f32_16x16x32_bf16 v[108:111], v[144:147], v[206:209], v[108:111]
	v_mfma_f32_16x16x32_bf16 v[104:107], v[136:139], v[214:217], v[104:107]
	v_mfma_f32_16x16x32_bf16 v[100:103], v[144:147], v[214:217], v[100:103]
	s_setprio 0
	s_setprio 1
	v_mfma_f32_16x16x32_bf16 v[96:99], v[148:151], v[186:189], v[96:99]
	v_mfma_f32_16x16x32_bf16 v[92:95], v[156:159], v[186:189], v[92:95]
	v_mfma_f32_16x16x32_bf16 v[88:91], v[148:151], v[194:197], v[88:91]
	v_mfma_f32_16x16x32_bf16 v[84:87], v[156:159], v[194:197], v[84:87]
	v_mfma_f32_16x16x32_bf16 v[80:83], v[148:151], v[202:205], v[80:83]
	v_mfma_f32_16x16x32_bf16 v[76:79], v[156:159], v[202:205], v[76:79]
	v_mfma_f32_16x16x32_bf16 v[72:75], v[148:151], v[210:213], v[72:75]
	v_mfma_f32_16x16x32_bf16 v[68:71], v[156:159], v[210:213], v[68:71]
	v_mfma_f32_16x16x32_bf16 v[96:99], v[152:155], v[190:193], v[96:99]
	v_mfma_f32_16x16x32_bf16 v[92:95], v[160:163], v[190:193], v[92:95]
	v_mfma_f32_16x16x32_bf16 v[88:91], v[152:155], v[198:201], v[88:91]
	v_mfma_f32_16x16x32_bf16 v[84:87], v[160:163], v[198:201], v[84:87]
	v_mfma_f32_16x16x32_bf16 v[80:83], v[152:155], v[206:209], v[80:83]
	v_mfma_f32_16x16x32_bf16 v[76:79], v[160:163], v[206:209], v[76:79]
	v_mfma_f32_16x16x32_bf16 v[72:75], v[152:155], v[214:217], v[72:75]
	v_mfma_f32_16x16x32_bf16 v[68:71], v[160:163], v[214:217], v[68:71]
	s_setprio 0
	s_barrier
	s_add_i32 s52, s85, s7
	s_mov_b32 m0, s52
	ds_read_b128 v[186:189], v185 offset:49152
	ds_read_b128 v[190:193], v251 offset:49152
	ds_read_b128 v[194:197], v185 offset:51200
	ds_read_b128 v[198:201], v251 offset:51200
	ds_read_b128 v[202:205], v185 offset:53248
	ds_read_b128 v[206:209], v251 offset:53248
	ds_read_b128 v[210:213], v185 offset:55296
	ds_read_b128 v[214:217], v251 offset:55296
	global_load_lds_dwordx4 v168, s[100:101]
	s_add_i32 m0, s52, 0x2000
	s_add_u32 s50, s50, 0x20080
	s_addc_u32 s51, s51, 0
	s_add_i32 s52, s86, s7
	global_load_lds_dwordx4 v172, s[100:101]
	s_mov_b32 m0, s52
	s_nop 0
	global_load_lds_dwordx4 v168, s[50:51]
	s_add_i32 m0, s52, 0x2000
	s_nop 0
	global_load_lds_dwordx4 v172, s[50:51]
	s_mov_b32 m0, s72
	s_nop 0
	global_load_lds_dwordx4 v166, s[98:99]
	s_mov_b32 m0, s73
	s_nop 0
	global_load_lds_dwordx4 v170, s[98:99]
	s_waitcnt vmcnt(8)
	s_waitcnt lgkmcnt(0)
	s_barrier
	s_setprio 1
	s_waitcnt lgkmcnt(0)
	v_mfma_f32_16x16x32_bf16 v[64:67], v[132:135], v[186:189], v[64:67]
	v_mfma_f32_16x16x32_bf16 v[60:63], v[140:143], v[186:189], v[60:63]
	v_mfma_f32_16x16x32_bf16 v[56:59], v[132:135], v[194:197], v[56:59]
	v_mfma_f32_16x16x32_bf16 v[52:55], v[140:143], v[194:197], v[52:55]
	v_mfma_f32_16x16x32_bf16 v[48:51], v[132:135], v[202:205], v[48:51]
	v_mfma_f32_16x16x32_bf16 v[44:47], v[140:143], v[202:205], v[44:47]
	v_mfma_f32_16x16x32_bf16 v[40:43], v[132:135], v[210:213], v[40:43]
	v_mfma_f32_16x16x32_bf16 v[36:39], v[140:143], v[210:213], v[36:39]
	v_mfma_f32_16x16x32_bf16 v[64:67], v[136:139], v[190:193], v[64:67]
	v_mfma_f32_16x16x32_bf16 v[60:63], v[144:147], v[190:193], v[60:63]
	v_mfma_f32_16x16x32_bf16 v[56:59], v[136:139], v[198:201], v[56:59]
	v_mfma_f32_16x16x32_bf16 v[52:55], v[144:147], v[198:201], v[52:55]
	v_mfma_f32_16x16x32_bf16 v[48:51], v[136:139], v[206:209], v[48:51]
	v_mfma_f32_16x16x32_bf16 v[44:47], v[144:147], v[206:209], v[44:47]
	v_mfma_f32_16x16x32_bf16 v[40:43], v[136:139], v[214:217], v[40:43]
	v_mfma_f32_16x16x32_bf16 v[36:39], v[144:147], v[214:217], v[36:39]
	s_setprio 0
	s_setprio 1
	v_mfma_f32_16x16x32_bf16 v[32:35], v[148:151], v[186:189], v[32:35]
	v_mfma_f32_16x16x32_bf16 v[28:31], v[156:159], v[186:189], v[28:31]
	v_mfma_f32_16x16x32_bf16 v[24:27], v[148:151], v[194:197], v[24:27]
	v_mfma_f32_16x16x32_bf16 v[20:23], v[156:159], v[194:197], v[20:23]
	v_mfma_f32_16x16x32_bf16 v[16:19], v[148:151], v[202:205], v[16:19]
	v_mfma_f32_16x16x32_bf16 v[12:15], v[156:159], v[202:205], v[12:15]
	v_mfma_f32_16x16x32_bf16 v[6:9], v[148:151], v[210:213], v[8:11]
	v_mfma_f32_16x16x32_bf16 v[2:5], v[156:159], v[210:213], v[2:5]
	v_mfma_f32_16x16x32_bf16 v[32:35], v[152:155], v[190:193], v[32:35]
	v_mfma_f32_16x16x32_bf16 v[28:31], v[160:163], v[190:193], v[28:31]
	v_mfma_f32_16x16x32_bf16 v[24:27], v[152:155], v[198:201], v[24:27]
	v_mfma_f32_16x16x32_bf16 v[20:23], v[160:163], v[198:201], v[20:23]
	v_mfma_f32_16x16x32_bf16 v[16:19], v[152:155], v[206:209], v[16:19]
	v_mfma_f32_16x16x32_bf16 v[12:15], v[160:163], v[206:209], v[12:15]
	v_mfma_f32_16x16x32_bf16 v[8:11], v[152:155], v[214:217], v[6:9]
	v_mfma_f32_16x16x32_bf16 v[4:7], v[160:163], v[214:217], v[2:5]
	s_setprio 0
	s_add_i32 s84, s84, 2
	s_add_u32 s48, s48, 0x100
	s_addc_u32 s49, s49, 0
	s_add_u32 s82, s82, 0x100
	s_addc_u32 s83, s83, 0
	s_cmp_gt_u32 s84, 5
	s_barrier
	s_cbranch_scc0 .LBB0_573
	s_and_b64 vcc, exec, s[20:21]
	s_cbranch_vccz .LBB0_576
	s_barrier

; #define PG8_STAGE(bufoff, gbase, voff) do { _Pragma("unroll") for (int _i = 0; _i < 2; ++_i) \
;         __builtin_amdgcn_global_load_lds((const unsigned*)((const char*)(gbase) + (voff)[_i]), (PG8_LAS unsigned*)(lds + (bufoff) + ldsw + _i * 8192), 16, 0, 0); } while (0)
; #define PG8_LDA(dst, b, h) do { _Pragma("unroll") for (int m = 0; m < 4; ++m) _Pragma("unroll") for (int k = 0; k < 2; ++k) dst[m][k] = *(const PG8_LAS bf16x8*)(lds + PG8_SA(b, h) + aoff + m * 2048 + k * 1024); } while (0)
; #define PG8_LDB(dst, b, h) do { _Pragma("unroll") for (int n = 0; n < 2; ++n) _Pragma("unroll") for (int k = 0; k < 2; ++k) dst[n][k] = *(const PG8_LAS bf16x8*)(lds + PG8_SB(b, h) + boff + n * 2048 + k * 1024); } while (0)
; #define PG8_MMA(ai, bj, At, Bt) do { __builtin_amdgcn_s_setprio(1); _Pragma("unroll") for (int m = 0; m < 4; ++m) _Pragma("unroll") for (int n = 0; n < 2; ++n) _Pragma("unroll") for (int k = 0; k < 2; ++k) \
;         acc[ai][bj][m][n] = __builtin_amdgcn_mfma_f32_16x16x32_bf16(Bt[n][k], At[m][k], acc[ai][bj][m][n], 0, 0, 0); __builtin_amdgcn_s_setprio(0); } while (0)
; #define PG8_WAIT_V(n) asm volatile("s_waitcnt vmcnt(" #n ")" ::: "memory")
; #define PG8_WAIT_L(n) asm volatile("s_waitcnt lgkmcnt(" #n ")" ::: "memory")
; #define PG8_BAR __builtin_amdgcn_s_barrier()
; #define PG8_SCHED __builtin_amdgcn_sched_barrier(0)
; template <class Epi, class Sched, bool ALIGN_EPI = false, bool SP2 = false>
; __device__ __forceinline__ void gemm_phase(PG8_LAS unsigned char* lds, const Gemm g, const Sched& S, const Epi& E) {
;     ...
;             PG8_LDB(B0, 0, 0); PG8_LDB(B1, 0, 1); PG8_SCHED; PG8_LDA(At, 0, 0); PG8_STAGE(PG8_SA(1, 1), a1 + hstep, voffA);
;             PG8_WAIT_V(8); PG8_WAIT_L(0); PG8_BAR; PG8_MMA(0, 0, At, B0); PG8_MMA(0, 1, At, B1); PG8_BAR; PG8_SCHED;
;             PG8_LDA(At, 0, 1); PG8_STAGE(PG8_SB(0, 0), b2, voffB); PG8_STAGE(PG8_SB(0, 1), b2 + hstep, voffB); PG8_STAGE(PG8_SA(0, 0), a2, voffA);
;             PG8_WAIT_V(8); PG8_WAIT_L(0); PG8_BAR; PG8_MMA(1, 0, At, B0); PG8_MMA(1, 1, At, B1); PG8_BAR; PG8_SCHED;
.LBB0_680:
	ds_read_b128 v[128:131], v168
	ds_read_b128 v[150:153], v249
	ds_read_b128 v[154:157], v168 offset:2048
	ds_read_b128 v[172:175], v249 offset:2048
	ds_read_b128 v[176:179], v169
	ds_read_b128 v[180:183], v250
	ds_read_b128 v[184:187], v169 offset:2048
	ds_read_b128 v[188:191], v250 offset:2048
	s_add_u32 s31, s46, 0xfffc0080
	s_addc_u32 s48, s47, -1
	s_cmp_eq_u32 s30, 12
	s_cselect_b32 s51, s37, s48
	s_cselect_b32 s50, s72, s31
	s_cselect_b32 s49, s39, s3
	s_cselect_b32 s48, s73, s74
	s_add_i32 m0, s8, 0xc000
	ds_read_b128 v[192:195], v170
	ds_read_b128 v[196:199], v251
	ds_read_b128 v[200:203], v170 offset:2048
	ds_read_b128 v[204:207], v251 offset:2048
	ds_read_b128 v[208:211], v170 offset:4096
	ds_read_b128 v[212:215], v251 offset:4096
	ds_read_b128 v[216:219], v170 offset:6144
	ds_read_b128 v[220:223], v251 offset:6144
	global_load_lds_dwordx4 v142, s[46:47]
	s_add_i32 m0, s8, 0xe000
	s_nop 0
	global_load_lds_dwordx4 v144, s[46:47]
	s_waitcnt vmcnt(8)
	s_waitcnt lgkmcnt(0)
	s_barrier
	s_setprio 1
	s_waitcnt lgkmcnt(0)
	v_mfma_f32_16x16x32_bf16 v[124:127], v[128:131], v[192:195], v[124:127]
	v_mfma_f32_16x16x32_bf16 v[120:123], v[154:157], v[192:195], v[120:123]
	v_mfma_f32_16x16x32_bf16 v[108:111], v[128:131], v[200:203], v[108:111]
	v_mfma_f32_16x16x32_bf16 v[104:107], v[154:157], v[200:203], v[104:107]
	v_mfma_f32_16x16x32_bf16 v[92:95], v[128:131], v[208:211], v[92:95]
	v_mfma_f32_16x16x32_bf16 v[88:91], v[154:157], v[208:211], v[88:91]
	v_mfma_f32_16x16x32_bf16 v[76:79], v[128:131], v[216:219], v[76:79]
	v_mfma_f32_16x16x32_bf16 v[72:75], v[154:157], v[216:219], v[72:75]
	v_mfma_f32_16x16x32_bf16 v[124:127], v[150:153], v[196:199], v[124:127]
	v_mfma_f32_16x16x32_bf16 v[120:123], v[172:175], v[196:199], v[120:123]
	v_mfma_f32_16x16x32_bf16 v[108:111], v[150:153], v[204:207], v[108:111]
	v_mfma_f32_16x16x32_bf16 v[104:107], v[172:175], v[204:207], v[104:107]
	v_mfma_f32_16x16x32_bf16 v[92:95], v[150:153], v[212:215], v[92:95]
	v_mfma_f32_16x16x32_bf16 v[88:91], v[172:175], v[212:215], v[88:91]
	v_mfma_f32_16x16x32_bf16 v[76:79], v[150:153], v[220:223], v[76:79]
	v_mfma_f32_16x16x32_bf16 v[72:75], v[172:175], v[220:223], v[72:75]
	s_setprio 0
	s_setprio 1
	v_mfma_f32_16x16x32_bf16 v[116:119], v[176:179], v[192:195], v[116:119]
	v_mfma_f32_16x16x32_bf16 v[112:115], v[184:187], v[192:195], v[112:115]
	v_mfma_f32_16x16x32_bf16 v[100:103], v[176:179], v[200:203], v[100:103]
	v_mfma_f32_16x16x32_bf16 v[96:99], v[184:187], v[200:203], v[96:99]
	v_mfma_f32_16x16x32_bf16 v[84:87], v[176:179], v[208:211], v[84:87]
	v_mfma_f32_16x16x32_bf16 v[80:83], v[184:187], v[208:211], v[80:83]
	v_mfma_f32_16x16x32_bf16 v[68:71], v[176:179], v[216:219], v[68:71]
	v_mfma_f32_16x16x32_bf16 v[64:67], v[184:187], v[216:219], v[64:67]
	v_mfma_f32_16x16x32_bf16 v[116:119], v[180:183], v[196:199], v[116:119]
	v_mfma_f32_16x16x32_bf16 v[112:115], v[188:191], v[196:199], v[112:115]
	v_mfma_f32_16x16x32_bf16 v[100:103], v[180:183], v[204:207], v[100:103]
	v_mfma_f32_16x16x32_bf16 v[96:99], v[188:191], v[204:207], v[96:99]
	v_mfma_f32_16x16x32_bf16 v[84:87], v[180:183], v[212:215], v[84:87]
	v_mfma_f32_16x16x32_bf16 v[80:83], v[188:191], v[212:215], v[80:83]
	v_mfma_f32_16x16x32_bf16 v[68:71], v[180:183], v[220:223], v[68:71]
	v_mfma_f32_16x16x32_bf16 v[64:67], v[188:191], v[220:223], v[64:67]
	s_setprio 0
	s_barrier
	s_add_i32 s31, s58, s7
	s_mov_b32 m0, s31
	ds_read_b128 v[192:195], v170 offset:16384
	ds_read_b128 v[196:199], v251 offset:16384
	ds_read_b128 v[200:203], v170 offset:18432
	ds_read_b128 v[204:207], v251 offset:18432
	ds_read_b128 v[208:211], v170 offset:20480
	ds_read_b128 v[212:215], v251 offset:20480
	ds_read_b128 v[216:219], v170 offset:22528
	ds_read_b128 v[220:223], v251 offset:22528
	global_load_lds_dwordx4 v134, s[48:49]
	s_add_i32 m0, s31, 0x2000
	s_add_u32 s76, s48, 0x40000
	s_addc_u32 s77, s49, 0
	s_add_i32 s31, s59, s7
	global_load_lds_dwordx4 v138, s[48:49]
	s_mov_b32 m0, s31
	s_nop 0
	global_load_lds_dwordx4 v134, s[76:77]
	s_add_i32 m0, s31, 0x2000
	s_nop 0
	global_load_lds_dwordx4 v138, s[76:77]
	s_mov_b32 m0, s8
	s_nop 0
	global_load_lds_dwordx4 v132, s[50:51]
	s_mov_b32 m0, s9
	s_nop 0
	global_load_lds_dwordx4 v136, s[50:51]
	s_waitcnt vmcnt(8)
	s_waitcnt lgkmcnt(0)
	s_barrier
	s_setprio 1
	s_waitcnt lgkmcnt(0)
	v_mfma_f32_16x16x32_bf16 v[60:63], v[128:131], v[192:195], v[60:63]
	v_mfma_f32_16x16x32_bf16 v[56:59], v[154:157], v[192:195], v[56:59]
	v_mfma_f32_16x16x32_bf16 v[44:47], v[128:131], v[200:203], v[44:47]
	v_mfma_f32_16x16x32_bf16 v[40:43], v[154:157], v[200:203], v[40:43]
	v_mfma_f32_16x16x32_bf16 v[28:31], v[128:131], v[208:211], v[28:31]
	v_mfma_f32_16x16x32_bf16 v[24:27], v[154:157], v[208:211], v[24:27]
	v_mfma_f32_16x16x32_bf16 v[16:19], v[128:131], v[216:219], v[16:19]
	v_mfma_f32_16x16x32_bf16 v[8:11], v[154:157], v[216:219], v[8:11]
	v_mfma_f32_16x16x32_bf16 v[60:63], v[150:153], v[196:199], v[60:63]
	v_mfma_f32_16x16x32_bf16 v[56:59], v[172:175], v[196:199], v[56:59]
	v_mfma_f32_16x16x32_bf16 v[44:47], v[150:153], v[204:207], v[44:47]
	v_mfma_f32_16x16x32_bf16 v[40:43], v[172:175], v[204:207], v[40:43]
	v_mfma_f32_16x16x32_bf16 v[28:31], v[150:153], v[212:215], v[28:31]
	v_mfma_f32_16x16x32_bf16 v[24:27], v[172:175], v[212:215], v[24:27]
	v_mfma_f32_16x16x32_bf16 v[16:19], v[150:153], v[220:223], v[16:19]
	v_mfma_f32_16x16x32_bf16 v[8:11], v[172:175], v[220:223], v[8:11]
	s_setprio 0
	s_setprio 1
	v_mfma_f32_16x16x32_bf16 v[52:55], v[176:179], v[192:195], v[52:55]
	v_mfma_f32_16x16x32_bf16 v[48:51], v[184:187], v[192:195], v[48:51]
	v_mfma_f32_16x16x32_bf16 v[36:39], v[176:179], v[200:203], v[36:39]
	v_mfma_f32_16x16x32_bf16 v[32:35], v[184:187], v[200:203], v[32:35]
	v_mfma_f32_16x16x32_bf16 v[20:23], v[176:179], v[208:211], v[20:23]
	v_mfma_f32_16x16x32_bf16 v[12:15], v[184:187], v[208:211], v[12:15]
	v_mfma_f32_16x16x32_bf16 v[4:7], v[176:179], v[216:219], v[4:7]
	v_mfma_f32_16x16x32_bf16 v[0:3], v[184:187], v[216:219], v[0:3]
	v_mfma_f32_16x16x32_bf16 v[52:55], v[180:183], v[196:199], v[52:55]
	v_mfma_f32_16x16x32_bf16 v[48:51], v[188:191], v[196:199], v[48:51]
	v_mfma_f32_16x16x32_bf16 v[36:39], v[180:183], v[204:207], v[36:39]
	v_mfma_f32_16x16x32_bf16 v[32:35], v[188:191], v[204:207], v[32:35]
	v_mfma_f32_16x16x32_bf16 v[20:23], v[180:183], v[212:215], v[20:23]
	v_mfma_f32_16x16x32_bf16 v[12:15], v[188:191], v[212:215], v[12:15]
	v_mfma_f32_16x16x32_bf16 v[4:7], v[180:183], v[220:223], v[4:7]
	v_mfma_f32_16x16x32_bf16 v[0:3], v[188:191], v[220:223], v[0:3]
	s_setprio 0
	s_barrier
; #define PG8_STAGE(bufoff, gbase, voff) do { _Pragma("unroll") for (int _i = 0; _i < 2; ++_i) \
;         __builtin_amdgcn_global_load_lds((const unsigned*)((const char*)(gbase) + (voff)[_i]), (PG8_LAS unsigned*)(lds + (bufoff) + ldsw + _i * 8192), 16, 0, 0); } while (0)
; #define PG8_LDA(dst, b, h) do { _Pragma("unroll") for (int m = 0; m < 4; ++m) _Pragma("unroll") for (int k = 0; k < 2; ++k) dst[m][k] = *(const PG8_LAS bf16x8*)(lds + PG8_SA(b, h) + aoff + m * 2048 + k * 1024); } while (0)
; #define PG8_LDB(dst, b, h) do { _Pragma("unroll") for (int n = 0; n < 2; ++n) _Pragma("unroll") for (int k = 0; k < 2; ++k) dst[n][k] = *(const PG8_LAS bf16x8*)(lds + PG8_SB(b, h) + boff + n * 2048 + k * 1024); } while (0)
; template <class Epi, class Sched, bool ALIGN_EPI = false, bool SP2 = false>
; __device__ __forceinline__ void gemm_phase(PG8_LAS unsigned char* lds, const Gemm g, const Sched& S, const Epi& E) {
;     ...
;         for (int t = 0; t < nt; t += 2) {
;             const bool last = (t == nt - 2);
;             const char* a1 = cA + (size_t)(t + 1) * kstep;
;             const char* a2 = last ? nA : cA + (size_t)(t + 2) * kstep; const char* b2 = last ? nB : cB + (size_t)(t + 2) * kstep;
;             const char* a3 = a2 + kstep; const char* b3 = b2 + kstep;
;             if (last && has_next) S.a_ready(nxt);
;             if constexpr (SP2) {
;             PG8_LDB(B0, 0, 0); PG8_LDB(B1, 0, 1); PG8_SCHED; PG8_LDA(At, 0, 0); PG8_STAGE(PG8_SA(1, 1), a1 + hstep, voffA);
;             PG8_WAIT_V(8); PG8_WAIT_L(0); PG8_BAR; PG8_MMA(0, 0, At, B0); PG8_MMA(0, 1, At, B1); PG8_BAR; PG8_SCHED;
;             PG8_LDA(At, 0, 1); PG8_STAGE(PG8_SB(0, 0), b2, voffB); PG8_STAGE(PG8_SB(0, 1), b2 + hstep, voffB); PG8_STAGE(PG8_SA(0, 0), a2, voffA);
;             PG8_WAIT_V(8); PG8_WAIT_L(0); PG8_BAR; PG8_MMA(1, 0, At, B0); PG8_MMA(1, 1, At, B1); PG8_BAR; PG8_SCHED;
;             PG8_LDB(B0, 1, 0); PG8_LDB(B1, 1, 1); PG8_SCHED; PG8_LDA(At, 1, 0); PG8_STAGE(PG8_SA(0, 1), a2 + hstep, voffA);
;             PG8_WAIT_V(8); PG8_WAIT_L(0); PG8_BAR; PG8_MMA(0, 0, At, B0); PG8_MMA(0, 1, At, B1); PG8_BAR; PG8_SCHED;
;             PG8_LDA(At, 1, 1); PG8_STAGE(PG8_SB(1, 0), b3, voffB); PG8_STAGE(PG8_SB(1, 1), b3 + hstep, voffB); PG8_STAGE(PG8_SA(1, 0), a3, voffA);
;             PG8_WAIT_V(8); PG8_WAIT_L(0); PG8_BAR; PG8_MMA(1, 0, At, B0); PG8_MMA(1, 1, At, B1); PG8_BAR; PG8_SCHED;
	s_add_i32 s31, 0, 0x18000
	v_add_u32_e32 v165, s31, v166
	v_xor_b32_e32 v252, 64, v165
	s_add_i32 s75, 0, 0x1c000
	ds_read_b128 v[128:131], v165
	ds_read_b128 v[150:153], v252
	ds_read_b128 v[154:157], v165 offset:2048
	ds_read_b128 v[172:175], v252 offset:2048
	v_add_u32_e32 v165, s75, v166
	v_xor_b32_e32 v252, 64, v165
	ds_read_b128 v[176:179], v165
	ds_read_b128 v[180:183], v252
	ds_read_b128 v[184:187], v165 offset:2048
	ds_read_b128 v[188:191], v252 offset:2048
	s_add_u32 s50, s50, 0x40000
	s_addc_u32 s51, s51, 0
	s_mov_b32 m0, s34
	ds_read_b128 v[192:195], v170 offset:32768
	ds_read_b128 v[196:199], v251 offset:32768
	ds_read_b128 v[200:203], v170 offset:34816
	ds_read_b128 v[204:207], v251 offset:34816
	ds_read_b128 v[208:211], v170 offset:36864
	ds_read_b128 v[212:215], v251 offset:36864
	ds_read_b128 v[216:219], v170 offset:38912
	ds_read_b128 v[220:223], v251 offset:38912
	global_load_lds_dwordx4 v132, s[50:51]
	s_mov_b32 m0, s35
	s_nop 0
	global_load_lds_dwordx4 v136, s[50:51]
	s_add_u32 s100, s48, 0x80
	s_addc_u32 s101, s49, 0
	s_sub_u32 s98, s50, 0x3ff80
	s_subb_u32 s99, s51, 0
	s_waitcnt vmcnt(8)
	s_waitcnt lgkmcnt(0)
	s_barrier
	s_setprio 1
	s_waitcnt lgkmcnt(0)
	v_mfma_f32_16x16x32_bf16 v[124:127], v[128:131], v[192:195], v[124:127]
	v_mfma_f32_16x16x32_bf16 v[120:123], v[154:157], v[192:195], v[120:123]
	v_mfma_f32_16x16x32_bf16 v[108:111], v[128:131], v[200:203], v[108:111]
	v_mfma_f32_16x16x32_bf16 v[104:107], v[154:157], v[200:203], v[104:107]
	v_mfma_f32_16x16x32_bf16 v[92:95], v[128:131], v[208:211], v[92:95]
	v_mfma_f32_16x16x32_bf16 v[88:91], v[154:157], v[208:211], v[88:91]
	v_mfma_f32_16x16x32_bf16 v[76:79], v[128:131], v[216:219], v[76:79]
	v_mfma_f32_16x16x32_bf16 v[72:75], v[154:157], v[216:219], v[72:75]
	v_mfma_f32_16x16x32_bf16 v[124:127], v[150:153], v[196:199], v[124:127]
	v_mfma_f32_16x16x32_bf16 v[120:123], v[172:175], v[196:199], v[120:123]
	v_mfma_f32_16x16x32_bf16 v[108:111], v[150:153], v[204:207], v[108:111]
	v_mfma_f32_16x16x32_bf16 v[104:107], v[172:175], v[204:207], v[104:107]
	v_mfma_f32_16x16x32_bf16 v[92:95], v[150:153], v[212:215], v[92:95]
	v_mfma_f32_16x16x32_bf16 v[88:91], v[172:175], v[212:215], v[88:91]
	v_mfma_f32_16x16x32_bf16 v[76:79], v[150:153], v[220:223], v[76:79]
	v_mfma_f32_16x16x32_bf16 v[72:75], v[172:175], v[220:223], v[72:75]
	s_setprio 0
	s_setprio 1
	v_mfma_f32_16x16x32_bf16 v[116:119], v[176:179], v[192:195], v[116:119]
	v_mfma_f32_16x16x32_bf16 v[112:115], v[184:187], v[192:195], v[112:115]
	v_mfma_f32_16x16x32_bf16 v[100:103], v[176:179], v[200:203], v[100:103]
	v_mfma_f32_16x16x32_bf16 v[96:99], v[184:187], v[200:203], v[96:99]
	v_mfma_f32_16x16x32_bf16 v[84:87], v[176:179], v[208:211], v[84:87]
	v_mfma_f32_16x16x32_bf16 v[80:83], v[184:187], v[208:211], v[80:83]
	v_mfma_f32_16x16x32_bf16 v[68:71], v[176:179], v[216:219], v[68:71]
	v_mfma_f32_16x16x32_bf16 v[64:67], v[184:187], v[216:219], v[64:67]
	v_mfma_f32_16x16x32_bf16 v[116:119], v[180:183], v[196:199], v[116:119]
	v_mfma_f32_16x16x32_bf16 v[112:115], v[188:191], v[196:199], v[112:115]
	v_mfma_f32_16x16x32_bf16 v[100:103], v[180:183], v[204:207], v[100:103]
	v_mfma_f32_16x16x32_bf16 v[96:99], v[188:191], v[204:207], v[96:99]
	v_mfma_f32_16x16x32_bf16 v[84:87], v[180:183], v[212:215], v[84:87]
	v_mfma_f32_16x16x32_bf16 v[80:83], v[188:191], v[212:215], v[80:83]
	v_mfma_f32_16x16x32_bf16 v[68:71], v[180:183], v[220:223], v[68:71]
	v_mfma_f32_16x16x32_bf16 v[64:67], v[188:191], v[220:223], v[64:67]
	s_setprio 0
	s_barrier
	s_add_i32 s31, s31, s7
	s_mov_b32 m0, s31
	ds_read_b128 v[192:195], v170 offset:49152
	ds_read_b128 v[196:199], v251 offset:49152
	ds_read_b128 v[200:203], v170 offset:51200
	ds_read_b128 v[204:207], v251 offset:51200
	ds_read_b128 v[208:211], v170 offset:53248
	ds_read_b128 v[212:215], v251 offset:53248
	ds_read_b128 v[216:219], v170 offset:55296
	ds_read_b128 v[220:223], v251 offset:55296
	global_load_lds_dwordx4 v134, s[100:101]
	s_add_i32 m0, s31, 0x2000
	s_add_u32 s48, s48, 0x40080
	s_addc_u32 s49, s49, 0
	s_add_i32 s31, s75, s7
	global_load_lds_dwordx4 v138, s[100:101]
	s_mov_b32 m0, s31
	s_nop 0
	global_load_lds_dwordx4 v134, s[48:49]
	s_add_i32 m0, s31, 0x2000
	s_nop 0
	global_load_lds_dwordx4 v138, s[48:49]
	s_mov_b32 m0, s53
	s_nop 0
	global_load_lds_dwordx4 v132, s[98:99]
	s_mov_b32 m0, s54
	s_nop 0
	global_load_lds_dwordx4 v136, s[98:99]
	s_waitcnt vmcnt(8)
	s_waitcnt lgkmcnt(0)
	s_barrier
	s_setprio 1
	s_waitcnt lgkmcnt(0)
	v_mfma_f32_16x16x32_bf16 v[60:63], v[128:131], v[192:195], v[60:63]
	v_mfma_f32_16x16x32_bf16 v[56:59], v[154:157], v[192:195], v[56:59]
	v_mfma_f32_16x16x32_bf16 v[44:47], v[128:131], v[200:203], v[44:47]
	v_mfma_f32_16x16x32_bf16 v[40:43], v[154:157], v[200:203], v[40:43]
	v_mfma_f32_16x16x32_bf16 v[28:31], v[128:131], v[208:211], v[28:31]
	v_mfma_f32_16x16x32_bf16 v[24:27], v[154:157], v[208:211], v[24:27]
	v_mfma_f32_16x16x32_bf16 v[16:19], v[128:131], v[216:219], v[16:19]
	v_mfma_f32_16x16x32_bf16 v[8:11], v[154:157], v[216:219], v[8:11]
	v_mfma_f32_16x16x32_bf16 v[60:63], v[150:153], v[196:199], v[60:63]
	v_mfma_f32_16x16x32_bf16 v[56:59], v[172:175], v[196:199], v[56:59]
	v_mfma_f32_16x16x32_bf16 v[44:47], v[150:153], v[204:207], v[44:47]
	v_mfma_f32_16x16x32_bf16 v[40:43], v[172:175], v[204:207], v[40:43]
	v_mfma_f32_16x16x32_bf16 v[28:31], v[150:153], v[212:215], v[28:31]
	v_mfma_f32_16x16x32_bf16 v[24:27], v[172:175], v[212:215], v[24:27]
	v_mfma_f32_16x16x32_bf16 v[16:19], v[150:153], v[220:223], v[16:19]
	v_mfma_f32_16x16x32_bf16 v[8:11], v[172:175], v[220:223], v[8:11]
	s_setprio 0
	s_setprio 1
	v_mfma_f32_16x16x32_bf16 v[52:55], v[176:179], v[192:195], v[52:55]
	v_mfma_f32_16x16x32_bf16 v[48:51], v[184:187], v[192:195], v[48:51]
	v_mfma_f32_16x16x32_bf16 v[36:39], v[176:179], v[200:203], v[36:39]
	v_mfma_f32_16x16x32_bf16 v[32:35], v[184:187], v[200:203], v[32:35]
	v_mfma_f32_16x16x32_bf16 v[20:23], v[176:179], v[208:211], v[20:23]
	v_mfma_f32_16x16x32_bf16 v[12:15], v[184:187], v[208:211], v[12:15]
	v_mfma_f32_16x16x32_bf16 v[4:7], v[176:179], v[216:219], v[4:7]
	v_mfma_f32_16x16x32_bf16 v[0:3], v[184:187], v[216:219], v[0:3]
	v_mfma_f32_16x16x32_bf16 v[52:55], v[180:183], v[196:199], v[52:55]
	v_mfma_f32_16x16x32_bf16 v[48:51], v[188:191], v[196:199], v[48:51]
	v_mfma_f32_16x16x32_bf16 v[36:39], v[180:183], v[204:207], v[36:39]
	v_mfma_f32_16x16x32_bf16 v[32:35], v[188:191], v[204:207], v[32:35]
	v_mfma_f32_16x16x32_bf16 v[20:23], v[180:183], v[212:215], v[20:23]
	v_mfma_f32_16x16x32_bf16 v[12:15], v[188:191], v[212:215], v[12:15]
	v_mfma_f32_16x16x32_bf16 v[4:7], v[180:183], v[220:223], v[4:7]
	v_mfma_f32_16x16x32_bf16 v[0:3], v[188:191], v[220:223], v[0:3]
	s_setprio 0
	s_add_i32 s30, s30, 2
	s_add_u32 s46, s46, 0x100
	s_addc_u32 s47, s47, 0
	s_add_u32 s74, s74, 0x100
	s_addc_u32 s3, s3, 0
	s_cmp_gt_u32 s30, 13
	s_barrier
	s_cbranch_scc0 .LBB0_680
	s_and_b64 vcc, exec, s[20:21]
	s_cbranch_vccz .LBB0_683
	s_barrier

; #define PG8_STAGE(bufoff, gbase, voff) do { _Pragma("unroll") for (int _i = 0; _i < 2; ++_i) \
;         __builtin_amdgcn_global_load_lds((const unsigned*)((const char*)(gbase) + (voff)[_i]), (PG8_LAS unsigned*)(lds + (bufoff) + ldsw + _i * 8192), 16, 0, 0); } while (0)
; #define PG8_LDA(dst, b, h) do { _Pragma("unroll") for (int m = 0; m < 4; ++m) _Pragma("unroll") for (int k = 0; k < 2; ++k) dst[m][k] = *(const PG8_LAS bf16x8*)(lds + PG8_SA(b, h) + aoff + m * 2048 + k * 1024); } while (0)
; #define PG8_LDB(dst, b, h) do { _Pragma("unroll") for (int n = 0; n < 2; ++n) _Pragma("unroll") for (int k = 0; k < 2; ++k) dst[n][k] = *(const PG8_LAS bf16x8*)(lds + PG8_SB(b, h) + boff + n * 2048 + k * 1024); } while (0)
; #define PG8_MMA(ai, bj, At, Bt) do { __builtin_amdgcn_s_setprio(1); _Pragma("unroll") for (int m = 0; m < 4; ++m) _Pragma("unroll") for (int n = 0; n < 2; ++n) _Pragma("unroll") for (int k = 0; k < 2; ++k) \
;         acc[ai][bj][m][n] = __builtin_amdgcn_mfma_f32_16x16x32_bf16(Bt[n][k], At[m][k], acc[ai][bj][m][n], 0, 0, 0); __builtin_amdgcn_s_setprio(0); } while (0)
; #define PG8_WAIT_V(n) asm volatile("s_waitcnt vmcnt(" #n ")" ::: "memory")
; #define PG8_WAIT_L(n) asm volatile("s_waitcnt lgkmcnt(" #n ")" ::: "memory")
; #define PG8_BAR __builtin_amdgcn_s_barrier()
; #define PG8_SCHED __builtin_amdgcn_sched_barrier(0)
; template <class Epi, class Sched, bool ALIGN_EPI = false, bool SP2 = false>
; __device__ __forceinline__ void gemm_phase(PG8_LAS unsigned char* lds, const Gemm g, const Sched& S, const Epi& E) {
;     ...
;             PG8_LDB(B0, 0, 0); PG8_LDB(B1, 0, 1); PG8_SCHED; PG8_LDA(At, 0, 0); PG8_STAGE(PG8_SA(1, 1), a1 + hstep, voffA);
;             PG8_WAIT_V(8); PG8_WAIT_L(0); PG8_BAR; PG8_MMA(0, 0, At, B0); PG8_MMA(0, 1, At, B1); PG8_BAR; PG8_SCHED;
;             PG8_LDA(At, 0, 1); PG8_STAGE(PG8_SB(0, 0), b2, voffB); PG8_STAGE(PG8_SB(0, 1), b2 + hstep, voffB); PG8_STAGE(PG8_SA(0, 0), a2, voffA);
;             PG8_WAIT_V(8); PG8_WAIT_L(0); PG8_BAR; PG8_MMA(1, 0, At, B0); PG8_MMA(1, 1, At, B1); PG8_BAR; PG8_SCHED;
.LBB0_771:
	ds_read_b128 v[144:147], v151
	ds_read_b128 v[156:159], v249
	ds_read_b128 v[160:163], v151 offset:2048
	ds_read_b128 v[166:169], v249 offset:2048
	ds_read_b128 v[170:173], v152
	ds_read_b128 v[174:177], v250
	ds_read_b128 v[178:181], v152 offset:2048
	ds_read_b128 v[182:185], v250 offset:2048
	s_add_u32 s31, s38, 0xfffc0080
	s_addc_u32 s40, s39, -1
	s_cmp_eq_u32 s30, 12
	s_cselect_b32 s43, s21, s40
	s_cselect_b32 s42, s53, s31
	s_cselect_b32 s41, s23, s3
	s_cselect_b32 s40, s54, s55
	s_add_i32 m0, s8, 0xc000
	ds_read_b128 v[186:189], v153
	ds_read_b128 v[190:193], v251
	ds_read_b128 v[194:197], v153 offset:2048
	ds_read_b128 v[198:201], v251 offset:2048
	ds_read_b128 v[202:205], v153 offset:4096
	ds_read_b128 v[206:209], v251 offset:4096
	ds_read_b128 v[210:213], v153 offset:6144
	ds_read_b128 v[214:217], v251 offset:6144
	global_load_lds_dwordx4 v136, s[38:39]
	s_add_i32 m0, s8, 0xe000
	s_nop 0
	global_load_lds_dwordx4 v138, s[38:39]
	s_waitcnt vmcnt(8)
	s_waitcnt lgkmcnt(0)
	s_barrier
	s_setprio 1
	s_waitcnt lgkmcnt(0)
	v_mfma_f32_16x16x32_bf16 v[124:127], v[144:147], v[186:189], v[124:127]
	v_mfma_f32_16x16x32_bf16 v[120:123], v[160:163], v[186:189], v[120:123]
	v_mfma_f32_16x16x32_bf16 v[116:119], v[144:147], v[194:197], v[116:119]
	v_mfma_f32_16x16x32_bf16 v[104:107], v[160:163], v[194:197], v[104:107]
	v_mfma_f32_16x16x32_bf16 v[92:95], v[144:147], v[202:205], v[92:95]
	v_mfma_f32_16x16x32_bf16 v[88:91], v[160:163], v[202:205], v[88:91]
	v_mfma_f32_16x16x32_bf16 v[76:79], v[144:147], v[210:213], v[76:79]
	v_mfma_f32_16x16x32_bf16 v[72:75], v[160:163], v[210:213], v[72:75]
	v_mfma_f32_16x16x32_bf16 v[124:127], v[156:159], v[190:193], v[124:127]
	v_mfma_f32_16x16x32_bf16 v[120:123], v[166:169], v[190:193], v[120:123]
	v_mfma_f32_16x16x32_bf16 v[116:119], v[156:159], v[198:201], v[116:119]
	v_mfma_f32_16x16x32_bf16 v[104:107], v[166:169], v[198:201], v[104:107]
	v_mfma_f32_16x16x32_bf16 v[92:95], v[156:159], v[206:209], v[92:95]
	v_mfma_f32_16x16x32_bf16 v[88:91], v[166:169], v[206:209], v[88:91]
	v_mfma_f32_16x16x32_bf16 v[76:79], v[156:159], v[214:217], v[76:79]
	v_mfma_f32_16x16x32_bf16 v[72:75], v[166:169], v[214:217], v[72:75]
	s_setprio 0
	s_setprio 1
	v_mfma_f32_16x16x32_bf16 v[112:115], v[170:173], v[186:189], v[112:115]
	v_mfma_f32_16x16x32_bf16 v[108:111], v[178:181], v[186:189], v[108:111]
	v_mfma_f32_16x16x32_bf16 v[100:103], v[170:173], v[194:197], v[100:103]
	v_mfma_f32_16x16x32_bf16 v[96:99], v[178:181], v[194:197], v[96:99]
	v_mfma_f32_16x16x32_bf16 v[84:87], v[170:173], v[202:205], v[84:87]
	v_mfma_f32_16x16x32_bf16 v[80:83], v[178:181], v[202:205], v[80:83]
	v_mfma_f32_16x16x32_bf16 v[68:71], v[170:173], v[210:213], v[68:71]
	v_mfma_f32_16x16x32_bf16 v[64:67], v[178:181], v[210:213], v[64:67]
	v_mfma_f32_16x16x32_bf16 v[112:115], v[174:177], v[190:193], v[112:115]
	v_mfma_f32_16x16x32_bf16 v[108:111], v[182:185], v[190:193], v[108:111]
	v_mfma_f32_16x16x32_bf16 v[100:103], v[174:177], v[198:201], v[100:103]
	v_mfma_f32_16x16x32_bf16 v[96:99], v[182:185], v[198:201], v[96:99]
	v_mfma_f32_16x16x32_bf16 v[84:87], v[174:177], v[206:209], v[84:87]
	v_mfma_f32_16x16x32_bf16 v[80:83], v[182:185], v[206:209], v[80:83]
	v_mfma_f32_16x16x32_bf16 v[68:71], v[174:177], v[214:217], v[68:71]
	v_mfma_f32_16x16x32_bf16 v[64:67], v[182:185], v[214:217], v[64:67]
	s_setprio 0
	s_barrier
	s_add_i32 s31, s49, s6
	s_mov_b32 m0, s31
	ds_read_b128 v[186:189], v153 offset:16384
	ds_read_b128 v[190:193], v251 offset:16384
	ds_read_b128 v[194:197], v153 offset:18432
	ds_read_b128 v[198:201], v251 offset:18432
	ds_read_b128 v[202:205], v153 offset:20480
	ds_read_b128 v[206:209], v251 offset:20480
	ds_read_b128 v[210:213], v153 offset:22528
	ds_read_b128 v[214:217], v251 offset:22528
	global_load_lds_dwordx4 v132, s[40:41]
	s_add_i32 m0, s31, 0x2000
	s_add_u32 s58, s40, 0x40000
	s_addc_u32 s59, s41, 0
	s_add_i32 s31, s50, s6
	global_load_lds_dwordx4 v128, s[40:41]
	s_mov_b32 m0, s31
	s_nop 0
	global_load_lds_dwordx4 v132, s[58:59]
	s_add_i32 m0, s31, 0x2000
	s_nop 0
	global_load_lds_dwordx4 v128, s[58:59]
	s_mov_b32 m0, s8
	s_nop 0
	global_load_lds_dwordx4 v134, s[42:43]
	s_mov_b32 m0, s9
	s_nop 0
	global_load_lds_dwordx4 v130, s[42:43]
	s_waitcnt vmcnt(8)
	s_waitcnt lgkmcnt(0)
	s_barrier
	s_setprio 1
	s_waitcnt lgkmcnt(0)
	v_mfma_f32_16x16x32_bf16 v[60:63], v[144:147], v[186:189], v[60:63]
	v_mfma_f32_16x16x32_bf16 v[56:59], v[160:163], v[186:189], v[56:59]
	v_mfma_f32_16x16x32_bf16 v[44:47], v[144:147], v[194:197], v[44:47]
	v_mfma_f32_16x16x32_bf16 v[40:43], v[160:163], v[194:197], v[40:43]
	v_mfma_f32_16x16x32_bf16 v[28:31], v[144:147], v[202:205], v[28:31]
	v_mfma_f32_16x16x32_bf16 v[24:27], v[160:163], v[202:205], v[24:27]
	v_mfma_f32_16x16x32_bf16 v[12:15], v[144:147], v[210:213], v[12:15]
	v_mfma_f32_16x16x32_bf16 v[8:11], v[160:163], v[210:213], v[8:11]
	v_mfma_f32_16x16x32_bf16 v[60:63], v[156:159], v[190:193], v[60:63]
	v_mfma_f32_16x16x32_bf16 v[56:59], v[166:169], v[190:193], v[56:59]
	v_mfma_f32_16x16x32_bf16 v[44:47], v[156:159], v[198:201], v[44:47]
	v_mfma_f32_16x16x32_bf16 v[40:43], v[166:169], v[198:201], v[40:43]
	v_mfma_f32_16x16x32_bf16 v[28:31], v[156:159], v[206:209], v[28:31]
	v_mfma_f32_16x16x32_bf16 v[24:27], v[166:169], v[206:209], v[24:27]
	v_mfma_f32_16x16x32_bf16 v[12:15], v[156:159], v[214:217], v[12:15]
	v_mfma_f32_16x16x32_bf16 v[8:11], v[166:169], v[214:217], v[8:11]
	s_setprio 0
	s_setprio 1
	v_mfma_f32_16x16x32_bf16 v[52:55], v[170:173], v[186:189], v[52:55]
	v_mfma_f32_16x16x32_bf16 v[48:51], v[178:181], v[186:189], v[48:51]
	v_mfma_f32_16x16x32_bf16 v[36:39], v[170:173], v[194:197], v[36:39]
	v_mfma_f32_16x16x32_bf16 v[32:35], v[178:181], v[194:197], v[32:35]
	v_mfma_f32_16x16x32_bf16 v[20:23], v[170:173], v[202:205], v[20:23]
	v_mfma_f32_16x16x32_bf16 v[16:19], v[178:181], v[202:205], v[16:19]
	v_mfma_f32_16x16x32_bf16 v[4:7], v[170:173], v[210:213], v[4:7]
	v_mfma_f32_16x16x32_bf16 v[0:3], v[178:181], v[210:213], v[0:3]
	v_mfma_f32_16x16x32_bf16 v[52:55], v[174:177], v[190:193], v[52:55]
	v_mfma_f32_16x16x32_bf16 v[48:51], v[182:185], v[190:193], v[48:51]
	v_mfma_f32_16x16x32_bf16 v[36:39], v[174:177], v[198:201], v[36:39]
	v_mfma_f32_16x16x32_bf16 v[32:35], v[182:185], v[198:201], v[32:35]
	v_mfma_f32_16x16x32_bf16 v[20:23], v[174:177], v[206:209], v[20:23]
	v_mfma_f32_16x16x32_bf16 v[16:19], v[182:185], v[206:209], v[16:19]
	v_mfma_f32_16x16x32_bf16 v[4:7], v[174:177], v[214:217], v[4:7]
	v_mfma_f32_16x16x32_bf16 v[0:3], v[182:185], v[214:217], v[0:3]
	s_setprio 0
	s_barrier
; #define PG8_STAGE(bufoff, gbase, voff) do { _Pragma("unroll") for (int _i = 0; _i < 2; ++_i) \
;         __builtin_amdgcn_global_load_lds((const unsigned*)((const char*)(gbase) + (voff)[_i]), (PG8_LAS unsigned*)(lds + (bufoff) + ldsw + _i * 8192), 16, 0, 0); } while (0)
; #define PG8_LDA(dst, b, h) do { _Pragma("unroll") for (int m = 0; m < 4; ++m) _Pragma("unroll") for (int k = 0; k < 2; ++k) dst[m][k] = *(const PG8_LAS bf16x8*)(lds + PG8_SA(b, h) + aoff + m * 2048 + k * 1024); } while (0)
; #define PG8_LDB(dst, b, h) do { _Pragma("unroll") for (int n = 0; n < 2; ++n) _Pragma("unroll") for (int k = 0; k < 2; ++k) dst[n][k] = *(const PG8_LAS bf16x8*)(lds + PG8_SB(b, h) + boff + n * 2048 + k * 1024); } while (0)
; template <class Epi, class Sched, bool ALIGN_EPI = false, bool SP2 = false>
; __device__ __forceinline__ void gemm_phase(PG8_LAS unsigned char* lds, const Gemm g, const Sched& S, const Epi& E) {
;     ...
;         for (int t = 0; t < nt; t += 2) {
;             const bool last = (t == nt - 2);
;             const char* a1 = cA + (size_t)(t + 1) * kstep;
;             const char* a2 = last ? nA : cA + (size_t)(t + 2) * kstep; const char* b2 = last ? nB : cB + (size_t)(t + 2) * kstep;
;             const char* a3 = a2 + kstep; const char* b3 = b2 + kstep;
;             if (last && has_next) S.a_ready(nxt);
;             if constexpr (SP2) {
;             PG8_LDB(B0, 0, 0); PG8_LDB(B1, 0, 1); PG8_SCHED; PG8_LDA(At, 0, 0); PG8_STAGE(PG8_SA(1, 1), a1 + hstep, voffA);
;             PG8_WAIT_V(8); PG8_WAIT_L(0); PG8_BAR; PG8_MMA(0, 0, At, B0); PG8_MMA(0, 1, At, B1); PG8_BAR; PG8_SCHED;
;             PG8_LDA(At, 0, 1); PG8_STAGE(PG8_SB(0, 0), b2, voffB); PG8_STAGE(PG8_SB(0, 1), b2 + hstep, voffB); PG8_STAGE(PG8_SA(0, 0), a2, voffA);
;             PG8_WAIT_V(8); PG8_WAIT_L(0); PG8_BAR; PG8_MMA(1, 0, At, B0); PG8_MMA(1, 1, At, B1); PG8_BAR; PG8_SCHED;
;             PG8_LDB(B0, 1, 0); PG8_LDB(B1, 1, 1); PG8_SCHED; PG8_LDA(At, 1, 0); PG8_STAGE(PG8_SA(0, 1), a2 + hstep, voffA);
;             PG8_WAIT_V(8); PG8_WAIT_L(0); PG8_BAR; PG8_MMA(0, 0, At, B0); PG8_MMA(0, 1, At, B1); PG8_BAR; PG8_SCHED;
;             PG8_LDA(At, 1, 1); PG8_STAGE(PG8_SB(1, 0), b3, voffB); PG8_STAGE(PG8_SB(1, 1), b3 + hstep, voffB); PG8_STAGE(PG8_SA(1, 0), a3, voffA);
;             PG8_WAIT_V(8); PG8_WAIT_L(0); PG8_BAR; PG8_MMA(1, 0, At, B0); PG8_MMA(1, 1, At, B1); PG8_BAR; PG8_SCHED;
	s_add_i32 s31, 0, 0x18000
	v_add_u32_e32 v165, s31, v149
	v_xor_b32_e32 v252, 64, v165
	s_add_i32 s58, 0, 0x1c000
	ds_read_b128 v[144:147], v165
	ds_read_b128 v[156:159], v252
	ds_read_b128 v[160:163], v165 offset:2048
	ds_read_b128 v[166:169], v252 offset:2048
	v_add_u32_e32 v165, s58, v149
	v_xor_b32_e32 v252, 64, v165
	ds_read_b128 v[170:173], v165
	ds_read_b128 v[174:177], v252
	ds_read_b128 v[178:181], v165 offset:2048
	ds_read_b128 v[182:185], v252 offset:2048
	s_add_u32 s42, s42, 0x40000
	s_addc_u32 s43, s43, 0
	s_mov_b32 m0, s34
	ds_read_b128 v[186:189], v153 offset:32768
	ds_read_b128 v[190:193], v251 offset:32768
	ds_read_b128 v[194:197], v153 offset:34816
	ds_read_b128 v[198:201], v251 offset:34816
	ds_read_b128 v[202:205], v153 offset:36864
	ds_read_b128 v[206:209], v251 offset:36864
	ds_read_b128 v[210:213], v153 offset:38912
	ds_read_b128 v[214:217], v251 offset:38912
	global_load_lds_dwordx4 v134, s[42:43]
	s_mov_b32 m0, s35
	s_nop 0
	global_load_lds_dwordx4 v130, s[42:43]
	s_waitcnt vmcnt(8)
	s_waitcnt lgkmcnt(0)
	s_barrier
	s_setprio 1
	s_waitcnt lgkmcnt(0)
	v_mfma_f32_16x16x32_bf16 v[124:127], v[144:147], v[186:189], v[124:127]
	v_mfma_f32_16x16x32_bf16 v[120:123], v[160:163], v[186:189], v[120:123]
	v_mfma_f32_16x16x32_bf16 v[116:119], v[144:147], v[194:197], v[116:119]
	v_mfma_f32_16x16x32_bf16 v[104:107], v[160:163], v[194:197], v[104:107]
	v_mfma_f32_16x16x32_bf16 v[92:95], v[144:147], v[202:205], v[92:95]
	v_mfma_f32_16x16x32_bf16 v[88:91], v[160:163], v[202:205], v[88:91]
	v_mfma_f32_16x16x32_bf16 v[76:79], v[144:147], v[210:213], v[76:79]
	v_mfma_f32_16x16x32_bf16 v[72:75], v[160:163], v[210:213], v[72:75]
	v_mfma_f32_16x16x32_bf16 v[124:127], v[156:159], v[190:193], v[124:127]
	v_mfma_f32_16x16x32_bf16 v[120:123], v[166:169], v[190:193], v[120:123]
	v_mfma_f32_16x16x32_bf16 v[116:119], v[156:159], v[198:201], v[116:119]
	v_mfma_f32_16x16x32_bf16 v[104:107], v[166:169], v[198:201], v[104:107]
	v_mfma_f32_16x16x32_bf16 v[92:95], v[156:159], v[206:209], v[92:95]
	v_mfma_f32_16x16x32_bf16 v[88:91], v[166:169], v[206:209], v[88:91]
	v_mfma_f32_16x16x32_bf16 v[76:79], v[156:159], v[214:217], v[76:79]
	v_mfma_f32_16x16x32_bf16 v[72:75], v[166:169], v[214:217], v[72:75]
	s_setprio 0
	s_setprio 1
	v_mfma_f32_16x16x32_bf16 v[112:115], v[170:173], v[186:189], v[112:115]
	v_mfma_f32_16x16x32_bf16 v[108:111], v[178:181], v[186:189], v[108:111]
	v_mfma_f32_16x16x32_bf16 v[100:103], v[170:173], v[194:197], v[100:103]
	v_mfma_f32_16x16x32_bf16 v[96:99], v[178:181], v[194:197], v[96:99]
	v_mfma_f32_16x16x32_bf16 v[84:87], v[170:173], v[202:205], v[84:87]
	v_mfma_f32_16x16x32_bf16 v[80:83], v[178:181], v[202:205], v[80:83]
	v_mfma_f32_16x16x32_bf16 v[68:71], v[170:173], v[210:213], v[68:71]
	v_mfma_f32_16x16x32_bf16 v[64:67], v[178:181], v[210:213], v[64:67]
	v_mfma_f32_16x16x32_bf16 v[112:115], v[174:177], v[190:193], v[112:115]
	v_mfma_f32_16x16x32_bf16 v[108:111], v[182:185], v[190:193], v[108:111]
	v_mfma_f32_16x16x32_bf16 v[100:103], v[174:177], v[198:201], v[100:103]
	v_mfma_f32_16x16x32_bf16 v[96:99], v[182:185], v[198:201], v[96:99]
	v_mfma_f32_16x16x32_bf16 v[84:87], v[174:177], v[206:209], v[84:87]
	v_mfma_f32_16x16x32_bf16 v[80:83], v[182:185], v[206:209], v[80:83]
	v_mfma_f32_16x16x32_bf16 v[68:71], v[174:177], v[214:217], v[68:71]
	v_mfma_f32_16x16x32_bf16 v[64:67], v[182:185], v[214:217], v[64:67]
	s_setprio 0
	s_barrier
	s_add_i32 s31, s31, s6
	s_add_i32 m0, s31, 0xffffff80
	ds_read_b128 v[186:189], v153 offset:49152
	ds_read_b128 v[190:193], v251 offset:49152
	ds_read_b128 v[194:197], v153 offset:51200
	ds_read_b128 v[198:201], v251 offset:51200
	ds_read_b128 v[202:205], v153 offset:53248
	ds_read_b128 v[206:209], v251 offset:53248
	ds_read_b128 v[210:213], v153 offset:55296
	ds_read_b128 v[214:217], v251 offset:55296
	global_load_lds_dwordx4 v132, s[40:41] offset:128
	s_add_i32 m0, s31, 0x1f80
	s_add_i32 s31, s58, s6
	global_load_lds_dwordx4 v128, s[40:41] offset:128
	s_add_u32 s40, s40, 0x40080
	s_addc_u32 s41, s41, 0
	s_mov_b32 m0, s31
	s_nop 0
	global_load_lds_dwordx4 v132, s[40:41]
	s_add_i32 m0, s31, 0x2000
	s_nop 0
	global_load_lds_dwordx4 v128, s[40:41]
	s_sub_u32 s98, s42, 0x3ff80
	s_subb_u32 s99, s43, 0
	s_mov_b32 m0, s46
	s_nop 0
	global_load_lds_dwordx4 v134, s[98:99]
	s_mov_b32 m0, s47
	s_nop 0
	global_load_lds_dwordx4 v130, s[98:99]
	s_waitcnt vmcnt(8)
	s_waitcnt lgkmcnt(0)
	s_barrier
	s_setprio 1
	s_waitcnt lgkmcnt(0)
	v_mfma_f32_16x16x32_bf16 v[60:63], v[144:147], v[186:189], v[60:63]
	v_mfma_f32_16x16x32_bf16 v[56:59], v[160:163], v[186:189], v[56:59]
	v_mfma_f32_16x16x32_bf16 v[44:47], v[144:147], v[194:197], v[44:47]
	v_mfma_f32_16x16x32_bf16 v[40:43], v[160:163], v[194:197], v[40:43]
	v_mfma_f32_16x16x32_bf16 v[28:31], v[144:147], v[202:205], v[28:31]
	v_mfma_f32_16x16x32_bf16 v[24:27], v[160:163], v[202:205], v[24:27]
	v_mfma_f32_16x16x32_bf16 v[12:15], v[144:147], v[210:213], v[12:15]
	v_mfma_f32_16x16x32_bf16 v[8:11], v[160:163], v[210:213], v[8:11]
	v_mfma_f32_16x16x32_bf16 v[60:63], v[156:159], v[190:193], v[60:63]
	v_mfma_f32_16x16x32_bf16 v[56:59], v[166:169], v[190:193], v[56:59]
	v_mfma_f32_16x16x32_bf16 v[44:47], v[156:159], v[198:201], v[44:47]
	v_mfma_f32_16x16x32_bf16 v[40:43], v[166:169], v[198:201], v[40:43]
	v_mfma_f32_16x16x32_bf16 v[28:31], v[156:159], v[206:209], v[28:31]
	v_mfma_f32_16x16x32_bf16 v[24:27], v[166:169], v[206:209], v[24:27]
	v_mfma_f32_16x16x32_bf16 v[12:15], v[156:159], v[214:217], v[12:15]
	v_mfma_f32_16x16x32_bf16 v[8:11], v[166:169], v[214:217], v[8:11]
	s_setprio 0
	s_setprio 1
	v_mfma_f32_16x16x32_bf16 v[52:55], v[170:173], v[186:189], v[52:55]
	v_mfma_f32_16x16x32_bf16 v[48:51], v[178:181], v[186:189], v[48:51]
	v_mfma_f32_16x16x32_bf16 v[36:39], v[170:173], v[194:197], v[36:39]
	v_mfma_f32_16x16x32_bf16 v[32:35], v[178:181], v[194:197], v[32:35]
	v_mfma_f32_16x16x32_bf16 v[20:23], v[170:173], v[202:205], v[20:23]
	v_mfma_f32_16x16x32_bf16 v[16:19], v[178:181], v[202:205], v[16:19]
	v_mfma_f32_16x16x32_bf16 v[4:7], v[170:173], v[210:213], v[4:7]
	v_mfma_f32_16x16x32_bf16 v[0:3], v[178:181], v[210:213], v[0:3]
	v_mfma_f32_16x16x32_bf16 v[52:55], v[174:177], v[190:193], v[52:55]
	v_mfma_f32_16x16x32_bf16 v[48:51], v[182:185], v[190:193], v[48:51]
	v_mfma_f32_16x16x32_bf16 v[36:39], v[174:177], v[198:201], v[36:39]
	v_mfma_f32_16x16x32_bf16 v[32:35], v[182:185], v[198:201], v[32:35]
	v_mfma_f32_16x16x32_bf16 v[20:23], v[174:177], v[206:209], v[20:23]
	v_mfma_f32_16x16x32_bf16 v[16:19], v[182:185], v[206:209], v[16:19]
	v_mfma_f32_16x16x32_bf16 v[4:7], v[174:177], v[214:217], v[4:7]
	v_mfma_f32_16x16x32_bf16 v[0:3], v[182:185], v[214:217], v[0:3]
	s_setprio 0
	s_add_i32 s30, s30, 2
	s_add_u32 s38, s38, 0x100
	s_addc_u32 s39, s39, 0
	s_add_u32 s55, s55, 0x100
	s_addc_u32 s3, s3, 0
	s_cmp_gt_u32 s30, 13
	s_barrier
	s_cbranch_scc0 .LBB0_771
	s_and_b64 vcc, exec, s[18:19]
	s_cbranch_vccz .LBB0_774
	s_barrier

; #define PG8_STAGE(bufoff, gbase, voff) do { _Pragma("unroll") for (int _i = 0; _i < 2; ++_i) \
;         __builtin_amdgcn_global_load_lds((const unsigned*)((const char*)(gbase) + (voff)[_i]), (PG8_LAS unsigned*)(lds + (bufoff) + ldsw + _i * 8192), 16, 0, 0); } while (0)
; #define PG8_LDA(dst, b, h) do { _Pragma("unroll") for (int m = 0; m < 4; ++m) _Pragma("unroll") for (int k = 0; k < 2; ++k) dst[m][k] = *(const PG8_LAS bf16x8*)(lds + PG8_SA(b, h) + aoff + m * 2048 + k * 1024); } while (0)
; #define PG8_LDB(dst, b, h) do { _Pragma("unroll") for (int n = 0; n < 2; ++n) _Pragma("unroll") for (int k = 0; k < 2; ++k) dst[n][k] = *(const PG8_LAS bf16x8*)(lds + PG8_SB(b, h) + boff + n * 2048 + k * 1024); } while (0)
; #define PG8_MMA(ai, bj, At, Bt) do { __builtin_amdgcn_s_setprio(1); _Pragma("unroll") for (int m = 0; m < 4; ++m) _Pragma("unroll") for (int n = 0; n < 2; ++n) _Pragma("unroll") for (int k = 0; k < 2; ++k) \
;         acc[ai][bj][m][n] = __builtin_amdgcn_mfma_f32_16x16x32_bf16(Bt[n][k], At[m][k], acc[ai][bj][m][n], 0, 0, 0); __builtin_amdgcn_s_setprio(0); } while (0)
; #define PG8_WAIT_V(n) asm volatile("s_waitcnt vmcnt(" #n ")" ::: "memory")
; #define PG8_WAIT_L(n) asm volatile("s_waitcnt lgkmcnt(" #n ")" ::: "memory")
; #define PG8_BAR __builtin_amdgcn_s_barrier()
; #define PG8_SCHED __builtin_amdgcn_sched_barrier(0)
; template <class Epi, class Sched, bool ALIGN_EPI = false, bool SP2 = false>
; __device__ __forceinline__ void gemm_phase(PG8_LAS unsigned char* lds, const Gemm g, const Sched& S, const Epi& E) {
;     ...
;             PG8_LDB(B0, 0, 0); PG8_LDB(B1, 0, 1); PG8_SCHED; PG8_LDA(At, 0, 0); PG8_STAGE(PG8_SA(1, 1), a1 + hstep, voffA);
;             PG8_WAIT_V(8); PG8_WAIT_L(0); PG8_BAR; PG8_MMA(0, 0, At, B0); PG8_MMA(0, 1, At, B1); PG8_BAR; PG8_SCHED;
;             PG8_LDA(At, 0, 1); PG8_STAGE(PG8_SB(0, 0), b2, voffB); PG8_STAGE(PG8_SB(0, 1), b2 + hstep, voffB); PG8_STAGE(PG8_SA(0, 0), a2, voffA);
;             PG8_WAIT_V(8); PG8_WAIT_L(0); PG8_BAR; PG8_MMA(1, 0, At, B0); PG8_MMA(1, 1, At, B1); PG8_BAR; PG8_SCHED;
.LBB0_876:
	ds_read_b128 v[144:147], v153
	ds_read_b128 v[156:159], v249
	ds_read_b128 v[160:163], v153 offset:2048
	ds_read_b128 v[166:169], v249 offset:2048
	ds_read_b128 v[170:173], v154
	ds_read_b128 v[174:177], v250
	ds_read_b128 v[178:181], v154 offset:2048
	ds_read_b128 v[182:185], v250 offset:2048
	s_add_u32 s31, s34, 0xfff50080
	s_addc_u32 s36, s35, -1
	s_cmp_eq_u32 s30, 40
	s_cselect_b32 s39, s1, s36
	s_cselect_b32 s38, s0, s31
	s_cselect_b32 s37, s27, s54
	s_cselect_b32 s36, s26, s53
	s_add_i32 m0, s7, 0xc000
	ds_read_b128 v[186:189], v155
	ds_read_b128 v[190:193], v251
	ds_read_b128 v[194:197], v155 offset:2048
	ds_read_b128 v[198:201], v251 offset:2048
	ds_read_b128 v[202:205], v155 offset:4096
	ds_read_b128 v[206:209], v251 offset:4096
	ds_read_b128 v[210:213], v155 offset:6144
	ds_read_b128 v[214:217], v251 offset:6144
	global_load_lds_dwordx4 v136, s[34:35]
	s_add_i32 m0, s7, 0xe000
	s_nop 0
	global_load_lds_dwordx4 v138, s[34:35]
	s_waitcnt vmcnt(8)
	s_waitcnt lgkmcnt(0)
	s_barrier
	s_setprio 1
	s_waitcnt lgkmcnt(0)
	v_mfma_f32_16x16x32_bf16 v[124:127], v[144:147], v[186:189], v[124:127]
	v_mfma_f32_16x16x32_bf16 v[120:123], v[160:163], v[186:189], v[120:123]
	v_mfma_f32_16x16x32_bf16 v[112:115], v[144:147], v[194:197], v[112:115]
	v_mfma_f32_16x16x32_bf16 v[104:107], v[160:163], v[194:197], v[104:107]
	v_mfma_f32_16x16x32_bf16 v[96:99], v[144:147], v[202:205], v[96:99]
	v_mfma_f32_16x16x32_bf16 v[88:91], v[160:163], v[202:205], v[88:91]
	v_mfma_f32_16x16x32_bf16 v[80:83], v[144:147], v[210:213], v[80:83]
	v_mfma_f32_16x16x32_bf16 v[72:75], v[160:163], v[210:213], v[72:75]
	v_mfma_f32_16x16x32_bf16 v[124:127], v[156:159], v[190:193], v[124:127]
	v_mfma_f32_16x16x32_bf16 v[120:123], v[166:169], v[190:193], v[120:123]
	v_mfma_f32_16x16x32_bf16 v[112:115], v[156:159], v[198:201], v[112:115]
	v_mfma_f32_16x16x32_bf16 v[104:107], v[166:169], v[198:201], v[104:107]
	v_mfma_f32_16x16x32_bf16 v[96:99], v[156:159], v[206:209], v[96:99]
	v_mfma_f32_16x16x32_bf16 v[88:91], v[166:169], v[206:209], v[88:91]
	v_mfma_f32_16x16x32_bf16 v[80:83], v[156:159], v[214:217], v[80:83]
	v_mfma_f32_16x16x32_bf16 v[72:75], v[166:169], v[214:217], v[72:75]
	s_setprio 0
	s_setprio 1
	v_mfma_f32_16x16x32_bf16 v[116:119], v[170:173], v[186:189], v[116:119]
	v_mfma_f32_16x16x32_bf16 v[108:111], v[178:181], v[186:189], v[108:111]
	v_mfma_f32_16x16x32_bf16 v[100:103], v[170:173], v[194:197], v[100:103]
	v_mfma_f32_16x16x32_bf16 v[92:95], v[178:181], v[194:197], v[92:95]
	v_mfma_f32_16x16x32_bf16 v[84:87], v[170:173], v[202:205], v[84:87]
	v_mfma_f32_16x16x32_bf16 v[76:79], v[178:181], v[202:205], v[76:79]
	v_mfma_f32_16x16x32_bf16 v[68:71], v[170:173], v[210:213], v[68:71]
	v_mfma_f32_16x16x32_bf16 v[64:67], v[178:181], v[210:213], v[64:67]
	v_mfma_f32_16x16x32_bf16 v[116:119], v[174:177], v[190:193], v[116:119]
	v_mfma_f32_16x16x32_bf16 v[108:111], v[182:185], v[190:193], v[108:111]
	v_mfma_f32_16x16x32_bf16 v[100:103], v[174:177], v[198:201], v[100:103]
	v_mfma_f32_16x16x32_bf16 v[92:95], v[182:185], v[198:201], v[92:95]
	v_mfma_f32_16x16x32_bf16 v[84:87], v[174:177], v[206:209], v[84:87]
	v_mfma_f32_16x16x32_bf16 v[76:79], v[182:185], v[206:209], v[76:79]
	v_mfma_f32_16x16x32_bf16 v[68:71], v[174:177], v[214:217], v[68:71]
	v_mfma_f32_16x16x32_bf16 v[64:67], v[182:185], v[214:217], v[64:67]
	s_setprio 0
	s_barrier
	s_add_i32 s31, s47, s6
	s_mov_b32 m0, s31
	ds_read_b128 v[186:189], v155 offset:16384
	ds_read_b128 v[190:193], v251 offset:16384
	ds_read_b128 v[194:197], v155 offset:18432
	ds_read_b128 v[198:201], v251 offset:18432
	ds_read_b128 v[202:205], v155 offset:20480
	ds_read_b128 v[206:209], v251 offset:20480
	ds_read_b128 v[210:213], v155 offset:22528
	ds_read_b128 v[214:217], v251 offset:22528
	global_load_lds_dwordx4 v130, s[36:37]
	s_add_i32 m0, s31, 0x2000
	s_add_u32 s58, s36, 0xb0000
	s_addc_u32 s59, s37, 0
	s_add_i32 s31, s48, s6
	global_load_lds_dwordx4 v134, s[36:37]
	s_mov_b32 m0, s31
	s_nop 0
	global_load_lds_dwordx4 v130, s[58:59]
	s_add_i32 m0, s31, 0x2000
	s_nop 0
	global_load_lds_dwordx4 v134, s[58:59]
	s_mov_b32 m0, s7
	s_nop 0
	global_load_lds_dwordx4 v128, s[38:39]
	s_mov_b32 m0, s40
	s_nop 0
	global_load_lds_dwordx4 v132, s[38:39]
	s_waitcnt vmcnt(8)
	s_waitcnt lgkmcnt(0)
	s_barrier
	s_setprio 1
	s_waitcnt lgkmcnt(0)
	v_mfma_f32_16x16x32_bf16 v[60:63], v[144:147], v[186:189], v[60:63]
	v_mfma_f32_16x16x32_bf16 v[56:59], v[160:163], v[186:189], v[56:59]
	v_mfma_f32_16x16x32_bf16 v[48:51], v[144:147], v[194:197], v[48:51]
	v_mfma_f32_16x16x32_bf16 v[40:43], v[160:163], v[194:197], v[40:43]
	v_mfma_f32_16x16x32_bf16 v[32:35], v[144:147], v[202:205], v[32:35]
	v_mfma_f32_16x16x32_bf16 v[24:27], v[160:163], v[202:205], v[24:27]
	v_mfma_f32_16x16x32_bf16 v[16:19], v[144:147], v[210:213], v[16:19]
	v_mfma_f32_16x16x32_bf16 v[8:11], v[160:163], v[210:213], v[8:11]
	v_mfma_f32_16x16x32_bf16 v[60:63], v[156:159], v[190:193], v[60:63]
	v_mfma_f32_16x16x32_bf16 v[56:59], v[166:169], v[190:193], v[56:59]
	v_mfma_f32_16x16x32_bf16 v[48:51], v[156:159], v[198:201], v[48:51]
	v_mfma_f32_16x16x32_bf16 v[40:43], v[166:169], v[198:201], v[40:43]
	v_mfma_f32_16x16x32_bf16 v[32:35], v[156:159], v[206:209], v[32:35]
	v_mfma_f32_16x16x32_bf16 v[24:27], v[166:169], v[206:209], v[24:27]
	v_mfma_f32_16x16x32_bf16 v[16:19], v[156:159], v[214:217], v[16:19]
	v_mfma_f32_16x16x32_bf16 v[8:11], v[166:169], v[214:217], v[8:11]
	s_setprio 0
	s_setprio 1
	v_mfma_f32_16x16x32_bf16 v[52:55], v[170:173], v[186:189], v[52:55]
	v_mfma_f32_16x16x32_bf16 v[44:47], v[178:181], v[186:189], v[44:47]
	v_mfma_f32_16x16x32_bf16 v[36:39], v[170:173], v[194:197], v[36:39]
	v_mfma_f32_16x16x32_bf16 v[28:31], v[178:181], v[194:197], v[28:31]
	v_mfma_f32_16x16x32_bf16 v[20:23], v[170:173], v[202:205], v[20:23]
	v_mfma_f32_16x16x32_bf16 v[12:15], v[178:181], v[202:205], v[12:15]
	v_mfma_f32_16x16x32_bf16 v[4:7], v[170:173], v[210:213], v[4:7]
	v_mfma_f32_16x16x32_bf16 v[0:3], v[178:181], v[210:213], v[0:3]
	v_mfma_f32_16x16x32_bf16 v[52:55], v[174:177], v[190:193], v[52:55]
	v_mfma_f32_16x16x32_bf16 v[44:47], v[182:185], v[190:193], v[44:47]
	v_mfma_f32_16x16x32_bf16 v[36:39], v[174:177], v[198:201], v[36:39]
	v_mfma_f32_16x16x32_bf16 v[28:31], v[182:185], v[198:201], v[28:31]
	v_mfma_f32_16x16x32_bf16 v[20:23], v[174:177], v[206:209], v[20:23]
	v_mfma_f32_16x16x32_bf16 v[12:15], v[182:185], v[206:209], v[12:15]
	v_mfma_f32_16x16x32_bf16 v[4:7], v[174:177], v[214:217], v[4:7]
	v_mfma_f32_16x16x32_bf16 v[0:3], v[182:185], v[214:217], v[0:3]
	s_setprio 0
	s_barrier
; #define PG8_STAGE(bufoff, gbase, voff) do { _Pragma("unroll") for (int _i = 0; _i < 2; ++_i) \
;         __builtin_amdgcn_global_load_lds((const unsigned*)((const char*)(gbase) + (voff)[_i]), (PG8_LAS unsigned*)(lds + (bufoff) + ldsw + _i * 8192), 16, 0, 0); } while (0)
; #define PG8_LDA(dst, b, h) do { _Pragma("unroll") for (int m = 0; m < 4; ++m) _Pragma("unroll") for (int k = 0; k < 2; ++k) dst[m][k] = *(const PG8_LAS bf16x8*)(lds + PG8_SA(b, h) + aoff + m * 2048 + k * 1024); } while (0)
; #define PG8_LDB(dst, b, h) do { _Pragma("unroll") for (int n = 0; n < 2; ++n) _Pragma("unroll") for (int k = 0; k < 2; ++k) dst[n][k] = *(const PG8_LAS bf16x8*)(lds + PG8_SB(b, h) + boff + n * 2048 + k * 1024); } while (0)
; template <class Epi, class Sched, bool ALIGN_EPI = false, bool SP2 = false>
; __device__ __forceinline__ void gemm_phase(PG8_LAS unsigned char* lds, const Gemm g, const Sched& S, const Epi& E) {
;     ...
;         for (int t = 0; t < nt; t += 2) {
;             const bool last = (t == nt - 2);
;             const char* a1 = cA + (size_t)(t + 1) * kstep;
;             const char* a2 = last ? nA : cA + (size_t)(t + 2) * kstep; const char* b2 = last ? nB : cB + (size_t)(t + 2) * kstep;
;             const char* a3 = a2 + kstep; const char* b3 = b2 + kstep;
;             if (last && has_next) S.a_ready(nxt);
;             if constexpr (SP2) {
;             PG8_LDB(B0, 0, 0); PG8_LDB(B1, 0, 1); PG8_SCHED; PG8_LDA(At, 0, 0); PG8_STAGE(PG8_SA(1, 1), a1 + hstep, voffA);
;             PG8_WAIT_V(8); PG8_WAIT_L(0); PG8_BAR; PG8_MMA(0, 0, At, B0); PG8_MMA(0, 1, At, B1); PG8_BAR; PG8_SCHED;
;             PG8_LDA(At, 0, 1); PG8_STAGE(PG8_SB(0, 0), b2, voffB); PG8_STAGE(PG8_SB(0, 1), b2 + hstep, voffB); PG8_STAGE(PG8_SA(0, 0), a2, voffA);
;             PG8_WAIT_V(8); PG8_WAIT_L(0); PG8_BAR; PG8_MMA(1, 0, At, B0); PG8_MMA(1, 1, At, B1); PG8_BAR; PG8_SCHED;
;             PG8_LDB(B0, 1, 0); PG8_LDB(B1, 1, 1); PG8_SCHED; PG8_LDA(At, 1, 0); PG8_STAGE(PG8_SA(0, 1), a2 + hstep, voffA);
;             PG8_WAIT_V(8); PG8_WAIT_L(0); PG8_BAR; PG8_MMA(0, 0, At, B0); PG8_MMA(0, 1, At, B1); PG8_BAR; PG8_SCHED;
;             PG8_LDA(At, 1, 1); PG8_STAGE(PG8_SB(1, 0), b3, voffB); PG8_STAGE(PG8_SB(1, 1), b3 + hstep, voffB); PG8_STAGE(PG8_SA(1, 0), a3, voffA);
;             PG8_WAIT_V(8); PG8_WAIT_L(0); PG8_BAR; PG8_MMA(1, 0, At, B0); PG8_MMA(1, 1, At, B1); PG8_BAR; PG8_SCHED;
	s_add_i32 s31, 0, 0x18000
	v_add_u32_e32 v165, s31, v151
	v_xor_b32_e32 v252, 64, v165
	s_add_i32 s55, 0, 0x1c000
	ds_read_b128 v[144:147], v165
	ds_read_b128 v[156:159], v252
	ds_read_b128 v[160:163], v165 offset:2048
	ds_read_b128 v[166:169], v252 offset:2048
	v_add_u32_e32 v165, s55, v151
	v_xor_b32_e32 v252, 64, v165
	ds_read_b128 v[170:173], v165
	ds_read_b128 v[174:177], v252
	ds_read_b128 v[178:181], v165 offset:2048
	ds_read_b128 v[182:185], v252 offset:2048
	s_add_u32 s38, s38, 0xb0000
	s_addc_u32 s39, s39, 0
	s_mov_b32 m0, s41
	ds_read_b128 v[186:189], v155 offset:32768
	ds_read_b128 v[190:193], v251 offset:32768
	ds_read_b128 v[194:197], v155 offset:34816
	ds_read_b128 v[198:201], v251 offset:34816
	ds_read_b128 v[202:205], v155 offset:36864
	ds_read_b128 v[206:209], v251 offset:36864
	ds_read_b128 v[210:213], v155 offset:38912
	ds_read_b128 v[214:217], v251 offset:38912
	global_load_lds_dwordx4 v128, s[38:39]
	s_mov_b32 m0, s42
	s_nop 0
	global_load_lds_dwordx4 v132, s[38:39]
	s_add_u32 s100, s36, 0x80
	s_addc_u32 s101, s37, 0
	s_sub_u32 s98, s38, 0xaff80
	s_subb_u32 s99, s39, 0
	s_waitcnt vmcnt(8)
	s_waitcnt lgkmcnt(0)
	s_barrier
	s_setprio 1
	s_waitcnt lgkmcnt(0)
	v_mfma_f32_16x16x32_bf16 v[124:127], v[144:147], v[186:189], v[124:127]
	v_mfma_f32_16x16x32_bf16 v[120:123], v[160:163], v[186:189], v[120:123]
	v_mfma_f32_16x16x32_bf16 v[112:115], v[144:147], v[194:197], v[112:115]
	v_mfma_f32_16x16x32_bf16 v[104:107], v[160:163], v[194:197], v[104:107]
	v_mfma_f32_16x16x32_bf16 v[96:99], v[144:147], v[202:205], v[96:99]
	v_mfma_f32_16x16x32_bf16 v[88:91], v[160:163], v[202:205], v[88:91]
	v_mfma_f32_16x16x32_bf16 v[80:83], v[144:147], v[210:213], v[80:83]
	v_mfma_f32_16x16x32_bf16 v[72:75], v[160:163], v[210:213], v[72:75]
	v_mfma_f32_16x16x32_bf16 v[124:127], v[156:159], v[190:193], v[124:127]
	v_mfma_f32_16x16x32_bf16 v[120:123], v[166:169], v[190:193], v[120:123]
	v_mfma_f32_16x16x32_bf16 v[112:115], v[156:159], v[198:201], v[112:115]
	v_mfma_f32_16x16x32_bf16 v[104:107], v[166:169], v[198:201], v[104:107]
	v_mfma_f32_16x16x32_bf16 v[96:99], v[156:159], v[206:209], v[96:99]
	v_mfma_f32_16x16x32_bf16 v[88:91], v[166:169], v[206:209], v[88:91]
	v_mfma_f32_16x16x32_bf16 v[80:83], v[156:159], v[214:217], v[80:83]
	v_mfma_f32_16x16x32_bf16 v[72:75], v[166:169], v[214:217], v[72:75]
	s_setprio 0
	s_setprio 1
	v_mfma_f32_16x16x32_bf16 v[116:119], v[170:173], v[186:189], v[116:119]
	v_mfma_f32_16x16x32_bf16 v[108:111], v[178:181], v[186:189], v[108:111]
	v_mfma_f32_16x16x32_bf16 v[100:103], v[170:173], v[194:197], v[100:103]
	v_mfma_f32_16x16x32_bf16 v[92:95], v[178:181], v[194:197], v[92:95]
	v_mfma_f32_16x16x32_bf16 v[84:87], v[170:173], v[202:205], v[84:87]
	v_mfma_f32_16x16x32_bf16 v[76:79], v[178:181], v[202:205], v[76:79]
	v_mfma_f32_16x16x32_bf16 v[68:71], v[170:173], v[210:213], v[68:71]
	v_mfma_f32_16x16x32_bf16 v[64:67], v[178:181], v[210:213], v[64:67]
	v_mfma_f32_16x16x32_bf16 v[116:119], v[174:177], v[190:193], v[116:119]
	v_mfma_f32_16x16x32_bf16 v[108:111], v[182:185], v[190:193], v[108:111]
	v_mfma_f32_16x16x32_bf16 v[100:103], v[174:177], v[198:201], v[100:103]
	v_mfma_f32_16x16x32_bf16 v[92:95], v[182:185], v[198:201], v[92:95]
	v_mfma_f32_16x16x32_bf16 v[84:87], v[174:177], v[206:209], v[84:87]
	v_mfma_f32_16x16x32_bf16 v[76:79], v[182:185], v[206:209], v[76:79]
	v_mfma_f32_16x16x32_bf16 v[68:71], v[174:177], v[214:217], v[68:71]
	v_mfma_f32_16x16x32_bf16 v[64:67], v[182:185], v[214:217], v[64:67]
	s_setprio 0
	s_barrier
	s_add_i32 s31, s31, s6
	s_mov_b32 m0, s31
	ds_read_b128 v[186:189], v155 offset:49152
	ds_read_b128 v[190:193], v251 offset:49152
	ds_read_b128 v[194:197], v155 offset:51200
	ds_read_b128 v[198:201], v251 offset:51200
	ds_read_b128 v[202:205], v155 offset:53248
	ds_read_b128 v[206:209], v251 offset:53248
	ds_read_b128 v[210:213], v155 offset:55296
	ds_read_b128 v[214:217], v251 offset:55296
	global_load_lds_dwordx4 v130, s[100:101]
	s_add_i32 m0, s31, 0x2000
	s_add_u32 s36, s36, 0xb0080
	s_addc_u32 s37, s37, 0
	s_add_i32 s31, s55, s6
	global_load_lds_dwordx4 v134, s[100:101]
	s_mov_b32 m0, s31
	s_nop 0
	global_load_lds_dwordx4 v130, s[36:37]
	s_add_i32 m0, s31, 0x2000
	s_nop 0
	global_load_lds_dwordx4 v134, s[36:37]
	s_mov_b32 m0, s44
	s_nop 0
	global_load_lds_dwordx4 v128, s[98:99]
	s_mov_b32 m0, s45
	s_nop 0
	global_load_lds_dwordx4 v132, s[98:99]
	s_waitcnt vmcnt(8)
	s_waitcnt lgkmcnt(0)
	s_barrier
	s_setprio 1
	s_waitcnt lgkmcnt(0)
	v_mfma_f32_16x16x32_bf16 v[60:63], v[144:147], v[186:189], v[60:63]
	v_mfma_f32_16x16x32_bf16 v[56:59], v[160:163], v[186:189], v[56:59]
	v_mfma_f32_16x16x32_bf16 v[48:51], v[144:147], v[194:197], v[48:51]
	v_mfma_f32_16x16x32_bf16 v[40:43], v[160:163], v[194:197], v[40:43]
	v_mfma_f32_16x16x32_bf16 v[32:35], v[144:147], v[202:205], v[32:35]
	v_mfma_f32_16x16x32_bf16 v[24:27], v[160:163], v[202:205], v[24:27]
	v_mfma_f32_16x16x32_bf16 v[16:19], v[144:147], v[210:213], v[16:19]
	v_mfma_f32_16x16x32_bf16 v[8:11], v[160:163], v[210:213], v[8:11]
	v_mfma_f32_16x16x32_bf16 v[60:63], v[156:159], v[190:193], v[60:63]
	v_mfma_f32_16x16x32_bf16 v[56:59], v[166:169], v[190:193], v[56:59]
	v_mfma_f32_16x16x32_bf16 v[48:51], v[156:159], v[198:201], v[48:51]
	v_mfma_f32_16x16x32_bf16 v[40:43], v[166:169], v[198:201], v[40:43]
	v_mfma_f32_16x16x32_bf16 v[32:35], v[156:159], v[206:209], v[32:35]
	v_mfma_f32_16x16x32_bf16 v[24:27], v[166:169], v[206:209], v[24:27]
	v_mfma_f32_16x16x32_bf16 v[16:19], v[156:159], v[214:217], v[16:19]
	v_mfma_f32_16x16x32_bf16 v[8:11], v[166:169], v[214:217], v[8:11]
	s_setprio 0
	s_setprio 1
	v_mfma_f32_16x16x32_bf16 v[52:55], v[170:173], v[186:189], v[52:55]
	v_mfma_f32_16x16x32_bf16 v[44:47], v[178:181], v[186:189], v[44:47]
	v_mfma_f32_16x16x32_bf16 v[36:39], v[170:173], v[194:197], v[36:39]
	v_mfma_f32_16x16x32_bf16 v[28:31], v[178:181], v[194:197], v[28:31]
	v_mfma_f32_16x16x32_bf16 v[20:23], v[170:173], v[202:205], v[20:23]
	v_mfma_f32_16x16x32_bf16 v[12:15], v[178:181], v[202:205], v[12:15]
	v_mfma_f32_16x16x32_bf16 v[4:7], v[170:173], v[210:213], v[4:7]
	v_mfma_f32_16x16x32_bf16 v[0:3], v[178:181], v[210:213], v[0:3]
	v_mfma_f32_16x16x32_bf16 v[52:55], v[174:177], v[190:193], v[52:55]
	v_mfma_f32_16x16x32_bf16 v[44:47], v[182:185], v[190:193], v[44:47]
	v_mfma_f32_16x16x32_bf16 v[36:39], v[174:177], v[198:201], v[36:39]
	v_mfma_f32_16x16x32_bf16 v[28:31], v[182:185], v[198:201], v[28:31]
	v_mfma_f32_16x16x32_bf16 v[20:23], v[174:177], v[206:209], v[20:23]
	v_mfma_f32_16x16x32_bf16 v[12:15], v[182:185], v[206:209], v[12:15]
	v_mfma_f32_16x16x32_bf16 v[4:7], v[174:177], v[214:217], v[4:7]
	v_mfma_f32_16x16x32_bf16 v[0:3], v[182:185], v[214:217], v[0:3]
	s_setprio 0
	s_add_i32 s30, s30, 2
	s_add_u32 s34, s34, 0x100
	s_addc_u32 s35, s35, 0
	s_add_u32 s53, s53, 0x100
	s_addc_u32 s54, s54, 0
	s_cmp_gt_u32 s30, 41
	s_barrier
	s_cbranch_scc0 .LBB0_876
	s_and_b64 vcc, exec, s[16:17]
	s_cbranch_vccz .LBB0_879
	s_barrier
